# DPP row_shr/quad_perm replaces ds_bpermute round trips in the LRU scan hops and the MoBA O-store epilogue (on top of final-norm pipelining + FFN-up param-load merge)
# speedup vs baseline: 1.0073x; 1.0007x over previous
.LBB0_542:
	v_cndmask_b32_e64 v149, v149, v190, s[42:43]
	v_mul_f32_e32 v149, 0xbe0293ee, v149
	v_fmamk_f32 v82, v82, 0x3e0293ee, v149
	v_fmamk_f32 v83, v83, 0x3e0293ee, v149
	v_fmamk_f32 v158, v95, 0x3e0293ee, v149
	v_fmamk_f32 v95, v76, 0x3e0293ee, v149
	v_exp_f32_e32 v76, v82
	v_fmamk_f32 v84, v84, 0x3e0293ee, v149
	v_fmamk_f32 v159, v96, 0x3e0293ee, v149
	v_fmamk_f32 v96, v77, 0x3e0293ee, v149
	v_exp_f32_e32 v77, v83
	v_fmamk_f32 v85, v85, 0x3e0293ee, v149
	v_fmamk_f32 v160, v97, 0x3e0293ee, v149
	v_fmamk_f32 v97, v78, 0x3e0293ee, v149
	v_exp_f32_e32 v78, v84
	v_fmamk_f32 v86, v86, 0x3e0293ee, v149
	v_fmamk_f32 v66, v66, 0x3e0293ee, v149
	v_exp_f32_e32 v82, v85
	v_fmamk_f32 v150, v87, 0x3e0293ee, v149
	v_fmamk_f32 v151, v88, 0x3e0293ee, v149
	v_fmamk_f32 v152, v89, 0x3e0293ee, v149
	v_fmamk_f32 v153, v90, 0x3e0293ee, v149
	v_fmamk_f32 v154, v91, 0x3e0293ee, v149
	v_fmamk_f32 v155, v92, 0x3e0293ee, v149
	v_fmamk_f32 v156, v93, 0x3e0293ee, v149
	v_fmamk_f32 v157, v94, 0x3e0293ee, v149
	v_fmamk_f32 v67, v67, 0x3e0293ee, v149
	v_fmamk_f32 v87, v68, 0x3e0293ee, v149
	v_fmamk_f32 v88, v69, 0x3e0293ee, v149
	v_fmamk_f32 v89, v70, 0x3e0293ee, v149
	v_fmamk_f32 v90, v71, 0x3e0293ee, v149
	v_fmamk_f32 v91, v72, 0x3e0293ee, v149
	v_fmamk_f32 v92, v73, 0x3e0293ee, v149
	v_fmamk_f32 v93, v74, 0x3e0293ee, v149
	v_fmamk_f32 v94, v75, 0x3e0293ee, v149
	v_exp_f32_e32 v83, v86
	v_fmamk_f32 v79, v79, 0x3e0293ee, v149
	v_fmamk_f32 v80, v80, 0x3e0293ee, v149
	v_fmac_f32_e32 v149, 0x3e0293ee, v81
	v_exp_f32_e32 v81, v66
	v_add_f32_e32 v66, 0, v76
	v_exp_f32_e32 v84, v150
	v_add_f32_e32 v66, v77, v66
	v_exp_f32_e32 v85, v151
	v_add_f32_e32 v66, v78, v66
	v_exp_f32_e32 v86, v152
	v_add_f32_e32 v66, v82, v66
	v_exp_f32_e32 v68, v153
	v_add_f32_e32 v66, v83, v66
	v_exp_f32_e32 v69, v154
	v_add_f32_e32 v66, v84, v66
	v_exp_f32_e32 v70, v155
	v_add_f32_e32 v66, v85, v66
	v_exp_f32_e32 v71, v156
	v_add_f32_e32 v66, v86, v66
	v_exp_f32_e32 v72, v157
	v_add_f32_e32 v66, v68, v66
	v_exp_f32_e32 v73, v158
	v_add_f32_e32 v66, v69, v66
	v_exp_f32_e32 v74, v159
	v_add_f32_e32 v66, v70, v66
	v_exp_f32_e32 v75, v160
	v_add_f32_e32 v66, v71, v66
	v_add_f32_e32 v66, v72, v66
	v_exp_f32_e32 v150, v67
	v_add_f32_e32 v66, v73, v66
	v_exp_f32_e32 v87, v87
	v_add_f32_e32 v66, v74, v66
	v_exp_f32_e32 v88, v88
	v_add_f32_e32 v66, v75, v66
	v_exp_f32_e32 v89, v89
	v_add_f32_e32 v66, v81, v66
	v_exp_f32_e32 v90, v90
	v_add_f32_e32 v66, v150, v66
	v_exp_f32_e32 v91, v91
	v_add_f32_e32 v66, v87, v66
	v_exp_f32_e32 v92, v92
	v_add_f32_e32 v66, v88, v66
	v_exp_f32_e32 v93, v93
	v_add_f32_e32 v66, v89, v66
	v_exp_f32_e32 v94, v94
	v_add_f32_e32 v66, v90, v66
	v_exp_f32_e32 v95, v95
	v_add_f32_e32 v66, v91, v66
	v_exp_f32_e32 v96, v96
	v_add_f32_e32 v66, v92, v66
	v_exp_f32_e32 v97, v97
	v_add_f32_e32 v66, v93, v66
	v_exp_f32_e32 v151, v79
	v_add_f32_e32 v66, v94, v66
	v_exp_f32_e32 v152, v80
	v_add_f32_e32 v66, v95, v66
	v_exp_f32_e32 v149, v149
	v_add_f32_e32 v66, v96, v66
	v_add_f32_e32 v66, v97, v66
	v_add_f32_e32 v66, v151, v66
	v_add_f32_e32 v66, v152, v66
	v_add_f32_e32 v66, v149, v66
	v_mov_b32_e32 v67, v66
	s_nop 1
	v_permlane32_swap_b32_e32 v66, v67
	v_cvt_pk_bf16_f32 v76, v76, v77
	v_cvt_pk_bf16_f32 v77, v78, v82
	v_cvt_pk_bf16_f32 v78, v83, v84
	v_cvt_pk_bf16_f32 v79, v85, v86
	v_cvt_pk_bf16_f32 v68, v68, v69
	v_cvt_pk_bf16_f32 v69, v70, v71
	v_cvt_pk_bf16_f32 v70, v72, v73
	v_cvt_pk_bf16_f32 v71, v74, v75
	v_cvt_pk_bf16_f32 v72, v81, v150
	v_cvt_pk_bf16_f32 v73, v87, v88
	v_cvt_pk_bf16_f32 v74, v89, v90
	v_cvt_pk_bf16_f32 v75, v91, v92
	v_cvt_pk_bf16_f32 v80, v93, v94
	v_cvt_pk_bf16_f32 v81, v95, v96
	v_cvt_pk_bf16_f32 v82, v97, v151
	v_cvt_pk_bf16_f32 v83, v152, v149
	v_permlane32_swap_b32_e32 v76, v78
	v_permlane32_swap_b32_e32 v77, v79
	v_permlane32_swap_b32_e32 v68, v70
	v_permlane32_swap_b32_e32 v69, v71
	v_permlane32_swap_b32_e32 v72, v74
	v_permlane32_swap_b32_e32 v73, v75
	v_permlane32_swap_b32_e32 v80, v82
	v_permlane32_swap_b32_e32 v81, v83
	ds_read_b64_tr_b16 v[84:85], v175 offset:0x4000
	ds_read_b64_tr_b16 v[86:87], v175 offset:0x4800
	ds_read_b64_tr_b16 v[88:89], v175 offset:0x5000
	ds_read_b64_tr_b16 v[90:91], v175 offset:0x5800
	ds_read_b64_tr_b16 v[92:93], v175 offset:0x6000
	ds_read_b64_tr_b16 v[94:95], v175 offset:0x6800
	ds_read_b64_tr_b16 v[150:151], v175 offset:0x7000
	ds_read_b64_tr_b16 v[152:153], v175 offset:0x7800
	s_waitcnt lgkmcnt(0)
	s_nop 0
	v_mfma_f32_32x32x16_bf16 v[34:49], v[76:79], v[84:87], v[34:49]
	ds_read_b64_tr_b16 v[84:85], v175 offset:0x4200
	ds_read_b64_tr_b16 v[86:87], v175 offset:0x4a00
	v_mfma_f32_32x32x16_bf16 v[34:49], v[68:71], v[88:91], v[34:49]
	ds_read_b64_tr_b16 v[88:89], v175 offset:0x5200
	ds_read_b64_tr_b16 v[90:91], v175 offset:0x5a00
	v_mfma_f32_32x32x16_bf16 v[34:49], v[72:75], v[92:95], v[34:49]
	ds_read_b64_tr_b16 v[92:93], v175 offset:0x6200
	ds_read_b64_tr_b16 v[94:95], v175 offset:0x6a00
	v_mfma_f32_32x32x16_bf16 v[34:49], v[80:83], v[150:153], v[34:49]
	ds_read_b64_tr_b16 v[150:151], v175 offset:0x7200
	ds_read_b64_tr_b16 v[152:153], v175 offset:0x7a00
	s_waitcnt lgkmcnt(0)
	v_mfma_f32_32x32x16_bf16 v[50:65], v[76:79], v[84:87], v[50:65]
	ds_read_b64_tr_b16 v[84:85], v175 offset:0x4400
	ds_read_b64_tr_b16 v[86:87], v175 offset:0x4c00
	v_mfma_f32_32x32x16_bf16 v[50:65], v[68:71], v[88:91], v[50:65]
	ds_read_b64_tr_b16 v[88:89], v175 offset:0x5400
	ds_read_b64_tr_b16 v[90:91], v175 offset:0x5c00
	v_mfma_f32_32x32x16_bf16 v[50:65], v[72:75], v[92:95], v[50:65]
	ds_read_b64_tr_b16 v[92:93], v175 offset:0x6400
	ds_read_b64_tr_b16 v[94:95], v175 offset:0x6c00
	v_mfma_f32_32x32x16_bf16 v[50:65], v[80:83], v[150:153], v[50:65]
	ds_read_b64_tr_b16 v[150:151], v175 offset:0x7400
	ds_read_b64_tr_b16 v[152:153], v175 offset:0x7c00
	s_waitcnt lgkmcnt(0)
	v_mfma_f32_32x32x16_bf16 v[18:33], v[76:79], v[84:87], v[18:33]
	ds_read_b64_tr_b16 v[84:85], v175 offset:0x4600
	ds_read_b64_tr_b16 v[86:87], v175 offset:0x4e00
	v_mfma_f32_32x32x16_bf16 v[18:33], v[68:71], v[88:91], v[18:33]
	ds_read_b64_tr_b16 v[88:89], v175 offset:0x5600
	ds_read_b64_tr_b16 v[90:91], v175 offset:0x5e00
	v_mfma_f32_32x32x16_bf16 v[18:33], v[72:75], v[92:95], v[18:33]
	ds_read_b64_tr_b16 v[92:93], v175 offset:0x6600
	ds_read_b64_tr_b16 v[94:95], v175 offset:0x6e00
	v_mfma_f32_32x32x16_bf16 v[18:33], v[80:83], v[150:153], v[18:33]
	ds_read_b64_tr_b16 v[150:151], v175 offset:0x7600
	ds_read_b64_tr_b16 v[152:153], v175 offset:0x7e00
	s_waitcnt lgkmcnt(0)
	v_mfma_f32_32x32x16_bf16 v[2:17], v[76:79], v[84:87], v[2:17]
	v_mfma_f32_32x32x16_bf16 v[2:17], v[68:71], v[88:91], v[2:17]
	v_mfma_f32_32x32x16_bf16 v[2:17], v[72:75], v[92:95], v[2:17]
	v_mfma_f32_32x32x16_bf16 v[2:17], v[80:83], v[150:153], v[2:17]
	s_waitcnt vmcnt(8)
	s_waitcnt vmcnt(9)
	ds_write_b128 v178, v[138:141] offset:32768
	s_waitcnt vmcnt(8)
	ds_write_b128 v178, v[142:145] offset:40960
	s_and_saveexec_b64 s[6:7], s[40:41]
	v_add_f32_e32 v68, v146, v147
	v_fmac_f32_e32 v68, v179, v194
	v_add_f32_e32 v66, v66, v67
	v_fmac_f32_e32 v66, v68, v148
	ds_write_b32 v177, v66
	s_or_b64 exec, exec, s[6:7]
	s_waitcnt lgkmcnt(0)
	ds_read_b128 v[78:81], v176
	ds_read_b128 v[74:77], v176 offset:32
	s_lshl_b64 s[6:7], s[16:17], 23
	s_add_u32 s6, s14, s6
	s_addc_u32 s7, s15, s7
	s_waitcnt lgkmcnt(1)
	v_rcp_f32_e32 v84, v78
	s_add_u32 s6, s6, s12
	s_addc_u32 s7, s7, 0
	s_add_u32 s8, s6, 0x3dc00800
	v_lshlrev_b32_e32 v78, 2, v174
	s_addc_u32 s9, s7, 0
	s_ashr_i32 s23, s22, 31
	v_xor_b32_e32 v78, 4, v78
	v_mul_f32_e32 v34, v34, v84
	ds_read_b128 v[70:73], v176 offset:64
	ds_read_b128 v[66:69], v176 offset:96
	s_lshl_b64 s[6:7], s[22:23], 12
	s_waitcnt lgkmcnt(0)
	s_nop 1
	v_mov_b32_dpp v85, v34 quad_perm:[1,0,3,2] row_mask:0xf bank_mask:0xf
	s_add_u32 s6, s8, s6
	s_addc_u32 s7, s9, s7
	v_and_b32_e32 v82, 1, v163
	v_lshlrev_b32_e32 v202, 1, v162
	v_cmp_eq_u32_e64 s[40:41], 0, v82
	v_lshl_add_u64 v[82:83], s[6:7], 0, v[202:203]
	v_lshlrev_b32_e32 v202, 14, v165
	v_writelane_b32 v248, s8, 53
	v_lshl_add_u64 v[82:83], v[82:83], 0, v[202:203]
	v_writelane_b32 v248, s9, 54
	s_and_saveexec_b64 s[6:7], s[40:41]
	s_cbranch_execz .LBB0_546
	v_cvt_pk_bf16_f32 v34, v34, v85
	global_store_dword v[82:83], v34, off
.LBB0_546:
	s_or_b64 exec, exec, s[6:7]
	v_mul_f32_e32 v34, v50, v84
	s_nop 1
	v_mov_b32_dpp v50, v34 quad_perm:[1,0,3,2] row_mask:0xf bank_mask:0xf
	s_and_saveexec_b64 s[6:7], s[40:41]
	s_cbranch_execz .LBB0_548
	v_cvt_pk_bf16_f32 v34, v34, v50
	global_store_dword v[82:83], v34, off offset:64
.LBB0_548:
	s_or_b64 exec, exec, s[6:7]
	v_mul_f32_e32 v18, v18, v84
	s_nop 1
	v_mov_b32_dpp v34, v18 quad_perm:[1,0,3,2] row_mask:0xf bank_mask:0xf
	s_and_saveexec_b64 s[6:7], s[40:41]
	s_cbranch_execz .LBB0_550
	v_cvt_pk_bf16_f32 v18, v18, v34
	global_store_dword v[82:83], v18, off offset:128
.LBB0_550:
	s_or_b64 exec, exec, s[6:7]
	v_mul_f32_e32 v2, v2, v84
	s_nop 1
	v_mov_b32_dpp v18, v2 quad_perm:[1,0,3,2] row_mask:0xf bank_mask:0xf
	s_and_saveexec_b64 s[6:7], s[40:41]
	s_cbranch_execz .LBB0_552
	v_cvt_pk_bf16_f32 v2, v2, v18
	global_store_dword v[82:83], v2, off offset:192
.LBB0_552:
	s_or_b64 exec, exec, s[6:7]
	v_rcp_f32_e32 v2, v79
	s_nop 0
	v_mul_f32_e32 v18, v35, v2
	s_nop 1
	v_mov_b32_dpp v34, v18 quad_perm:[1,0,3,2] row_mask:0xf bank_mask:0xf
	s_and_saveexec_b64 s[6:7], s[40:41]
	s_cbranch_execz .LBB0_554
	v_cvt_pk_bf16_f32 v18, v18, v34
	v_add_co_u32_e32 v34, vcc, 0x1000, v82
	s_nop 1
	v_addc_co_u32_e32 v35, vcc, 0, v83, vcc
	global_store_dword v[34:35], v18, off
.LBB0_554:
	s_or_b64 exec, exec, s[6:7]
	v_mul_f32_e32 v18, v51, v2
	s_nop 1
	v_mov_b32_dpp v34, v18 quad_perm:[1,0,3,2] row_mask:0xf bank_mask:0xf
	s_and_saveexec_b64 s[6:7], s[40:41]
	s_cbranch_execz .LBB0_556
	v_cvt_pk_bf16_f32 v18, v18, v34
	v_add_co_u32_e32 v34, vcc, 0x1000, v82
	s_nop 1
	v_addc_co_u32_e32 v35, vcc, 0, v83, vcc
	global_store_dword v[34:35], v18, off offset:64
.LBB0_556:
	s_or_b64 exec, exec, s[6:7]
	v_mul_f32_e32 v18, v19, v2
	s_nop 1
	v_mov_b32_dpp v19, v18 quad_perm:[1,0,3,2] row_mask:0xf bank_mask:0xf
	s_and_saveexec_b64 s[6:7], s[40:41]
	s_cbranch_execz .LBB0_558
	v_cvt_pk_bf16_f32 v34, v18, v19
	v_add_co_u32_e32 v18, vcc, 0x1000, v82
	s_nop 1
	v_addc_co_u32_e32 v19, vcc, 0, v83, vcc
	global_store_dword v[18:19], v34, off offset:128
.LBB0_558:
	s_or_b64 exec, exec, s[6:7]
	v_mul_f32_e32 v2, v3, v2
	s_nop 1
	v_mov_b32_dpp v3, v2 quad_perm:[1,0,3,2] row_mask:0xf bank_mask:0xf
	s_and_saveexec_b64 s[6:7], s[40:41]
	s_cbranch_execz .LBB0_560
	v_cvt_pk_bf16_f32 v18, v2, v3
	v_add_co_u32_e32 v2, vcc, 0x1000, v82
	s_nop 1
	v_addc_co_u32_e32 v3, vcc, 0, v83, vcc
	global_store_dword v[2:3], v18, off offset:192
.LBB0_560:
	s_or_b64 exec, exec, s[6:7]
	v_rcp_f32_e32 v2, v80
	s_nop 0
	v_mul_f32_e32 v3, v36, v2
	s_nop 1
	v_mov_b32_dpp v18, v3 quad_perm:[1,0,3,2] row_mask:0xf bank_mask:0xf
	s_and_saveexec_b64 s[6:7], s[40:41]
	s_cbranch_execz .LBB0_562
	v_cvt_pk_bf16_f32 v3, v3, v18
	v_add_co_u32_e32 v18, vcc, 0x2000, v82
	s_nop 1
	v_addc_co_u32_e32 v19, vcc, 0, v83, vcc
	global_store_dword v[18:19], v3, off
.LBB0_562:
	s_or_b64 exec, exec, s[6:7]
	v_mul_f32_e32 v3, v52, v2
	s_nop 1
	v_mov_b32_dpp v18, v3 quad_perm:[1,0,3,2] row_mask:0xf bank_mask:0xf
	s_and_saveexec_b64 s[6:7], s[40:41]
	s_cbranch_execz .LBB0_564
	v_cvt_pk_bf16_f32 v3, v3, v18
	v_add_co_u32_e32 v18, vcc, 0x2000, v82
	s_nop 1
	v_addc_co_u32_e32 v19, vcc, 0, v83, vcc
	global_store_dword v[18:19], v3, off offset:64
.LBB0_564:
	s_or_b64 exec, exec, s[6:7]
	v_mul_f32_e32 v3, v20, v2
	s_nop 1
	v_mov_b32_dpp v18, v3 quad_perm:[1,0,3,2] row_mask:0xf bank_mask:0xf
	s_and_saveexec_b64 s[6:7], s[40:41]
	s_cbranch_execz .LBB0_566
	v_cvt_pk_bf16_f32 v3, v3, v18
	v_add_co_u32_e32 v18, vcc, 0x2000, v82
	s_nop 1
	v_addc_co_u32_e32 v19, vcc, 0, v83, vcc
	global_store_dword v[18:19], v3, off offset:128
.LBB0_566:
	s_or_b64 exec, exec, s[6:7]
	v_mul_f32_e32 v2, v4, v2
	s_nop 1
	v_mov_b32_dpp v3, v2 quad_perm:[1,0,3,2] row_mask:0xf bank_mask:0xf
	s_and_saveexec_b64 s[6:7], s[40:41]
	s_cbranch_execz .LBB0_568
	v_cvt_pk_bf16_f32 v4, v2, v3
	v_add_co_u32_e32 v2, vcc, 0x2000, v82
	s_nop 1
	v_addc_co_u32_e32 v3, vcc, 0, v83, vcc
	global_store_dword v[2:3], v4, off offset:192
.LBB0_568:
	s_or_b64 exec, exec, s[6:7]
	v_rcp_f32_e32 v2, v81
	s_nop 0
	v_mul_f32_e32 v3, v37, v2
	s_nop 1
	v_mov_b32_dpp v4, v3 quad_perm:[1,0,3,2] row_mask:0xf bank_mask:0xf
	s_and_saveexec_b64 s[6:7], s[40:41]
	s_cbranch_execz .LBB0_570
	v_add_co_u32_e32 v18, vcc, 0x3000, v82
	v_cvt_pk_bf16_f32 v3, v3, v4
	v_addc_co_u32_e32 v19, vcc, 0, v83, vcc
	global_store_dword v[18:19], v3, off
.LBB0_570:
	s_or_b64 exec, exec, s[6:7]
	v_mul_f32_e32 v3, v53, v2
	s_nop 1
	v_mov_b32_dpp v4, v3 quad_perm:[1,0,3,2] row_mask:0xf bank_mask:0xf
	s_and_saveexec_b64 s[6:7], s[40:41]
	s_cbranch_execz .LBB0_572
	v_add_co_u32_e32 v18, vcc, 0x3000, v82
	v_cvt_pk_bf16_f32 v3, v3, v4
	v_addc_co_u32_e32 v19, vcc, 0, v83, vcc
	global_store_dword v[18:19], v3, off offset:64
.LBB0_572:
	s_or_b64 exec, exec, s[6:7]
	v_mul_f32_e32 v3, v21, v2
	s_nop 1
	v_mov_b32_dpp v4, v3 quad_perm:[1,0,3,2] row_mask:0xf bank_mask:0xf
	s_and_saveexec_b64 s[6:7], s[40:41]
	s_cbranch_execz .LBB0_574
	v_add_co_u32_e32 v18, vcc, 0x3000, v82
	v_cvt_pk_bf16_f32 v3, v3, v4
	v_addc_co_u32_e32 v19, vcc, 0, v83, vcc
	global_store_dword v[18:19], v3, off offset:128
.LBB0_574:
	s_or_b64 exec, exec, s[6:7]
	v_mul_f32_e32 v2, v5, v2
	s_nop 1
	v_mov_b32_dpp v3, v2 quad_perm:[1,0,3,2] row_mask:0xf bank_mask:0xf
	s_and_saveexec_b64 s[6:7], s[40:41]
	s_cbranch_execz .LBB0_576
	v_cvt_pk_bf16_f32 v4, v2, v3
	v_add_co_u32_e32 v2, vcc, 0x3000, v82
	s_nop 1
	v_addc_co_u32_e32 v3, vcc, 0, v83, vcc
	global_store_dword v[2:3], v4, off offset:192
.LBB0_576:
	s_or_b64 exec, exec, s[6:7]
	v_rcp_f32_e32 v2, v74
	s_nop 0
	v_mul_f32_e32 v3, v38, v2
	s_nop 1
	v_mov_b32_dpp v4, v3 quad_perm:[1,0,3,2] row_mask:0xf bank_mask:0xf
	s_and_saveexec_b64 s[6:7], s[40:41]
	s_cbranch_execz .LBB0_578
	v_cvt_pk_bf16_f32 v3, v3, v4
	v_add_co_u32_e32 v4, vcc, 0x8000, v82
	s_nop 1
	v_addc_co_u32_e32 v5, vcc, 0, v83, vcc
	global_store_dword v[4:5], v3, off
.LBB0_578:
	s_or_b64 exec, exec, s[6:7]
	v_mul_f32_e32 v3, v54, v2
	s_nop 1
	v_mov_b32_dpp v4, v3 quad_perm:[1,0,3,2] row_mask:0xf bank_mask:0xf
	s_and_saveexec_b64 s[6:7], s[40:41]
	s_cbranch_execz .LBB0_580
	v_cvt_pk_bf16_f32 v3, v3, v4
	v_add_co_u32_e32 v4, vcc, 0x8000, v82
	s_nop 1
	v_addc_co_u32_e32 v5, vcc, 0, v83, vcc
	global_store_dword v[4:5], v3, off offset:64
.LBB0_580:
	s_or_b64 exec, exec, s[6:7]
	v_mul_f32_e32 v3, v22, v2
	s_nop 1
	v_mov_b32_dpp v4, v3 quad_perm:[1,0,3,2] row_mask:0xf bank_mask:0xf
	s_and_saveexec_b64 s[6:7], s[40:41]
	s_cbranch_execz .LBB0_582
	v_cvt_pk_bf16_f32 v3, v3, v4
	v_add_co_u32_e32 v4, vcc, 0x8000, v82
	s_nop 1
	v_addc_co_u32_e32 v5, vcc, 0, v83, vcc
	global_store_dword v[4:5], v3, off offset:128
.LBB0_582:
	s_or_b64 exec, exec, s[6:7]
	v_mul_f32_e32 v2, v6, v2
	s_nop 1
	v_mov_b32_dpp v3, v2 quad_perm:[1,0,3,2] row_mask:0xf bank_mask:0xf
	s_and_saveexec_b64 s[6:7], s[40:41]
	s_cbranch_execz .LBB0_584
	v_cvt_pk_bf16_f32 v4, v2, v3
	v_add_co_u32_e32 v2, vcc, 0x8000, v82
	s_nop 1
	v_addc_co_u32_e32 v3, vcc, 0, v83, vcc
	global_store_dword v[2:3], v4, off offset:192
.LBB0_584:
	s_or_b64 exec, exec, s[6:7]
	v_rcp_f32_e32 v2, v75
	s_nop 0
	v_mul_f32_e32 v3, v39, v2
	s_nop 1
	v_mov_b32_dpp v4, v3 quad_perm:[1,0,3,2] row_mask:0xf bank_mask:0xf
	s_and_saveexec_b64 s[6:7], s[40:41]
	s_cbranch_execz .LBB0_586
	v_cvt_pk_bf16_f32 v3, v3, v4
	v_add_co_u32_e32 v4, vcc, 0x9000, v82
	s_nop 1
	v_addc_co_u32_e32 v5, vcc, 0, v83, vcc
	global_store_dword v[4:5], v3, off
.LBB0_586:
	s_or_b64 exec, exec, s[6:7]
	v_mul_f32_e32 v3, v55, v2
	s_nop 1
	v_mov_b32_dpp v4, v3 quad_perm:[1,0,3,2] row_mask:0xf bank_mask:0xf
	s_and_saveexec_b64 s[6:7], s[40:41]
	s_cbranch_execz .LBB0_588
	v_cvt_pk_bf16_f32 v3, v3, v4
	v_add_co_u32_e32 v4, vcc, 0x9000, v82
	s_nop 1
	v_addc_co_u32_e32 v5, vcc, 0, v83, vcc
	global_store_dword v[4:5], v3, off offset:64
.LBB0_588:
	s_or_b64 exec, exec, s[6:7]
	v_mul_f32_e32 v3, v23, v2
	s_nop 1
	v_mov_b32_dpp v4, v3 quad_perm:[1,0,3,2] row_mask:0xf bank_mask:0xf
	s_and_saveexec_b64 s[6:7], s[40:41]
	s_cbranch_execz .LBB0_590
	v_cvt_pk_bf16_f32 v3, v3, v4
	v_add_co_u32_e32 v4, vcc, 0x9000, v82
	s_nop 1
	v_addc_co_u32_e32 v5, vcc, 0, v83, vcc
	global_store_dword v[4:5], v3, off offset:128
.LBB0_590:
	s_or_b64 exec, exec, s[6:7]
	v_mul_f32_e32 v2, v7, v2
	s_nop 1
	v_mov_b32_dpp v3, v2 quad_perm:[1,0,3,2] row_mask:0xf bank_mask:0xf
	s_and_saveexec_b64 s[6:7], s[40:41]
	s_cbranch_execz .LBB0_592
	v_cvt_pk_bf16_f32 v4, v2, v3
	v_add_co_u32_e32 v2, vcc, 0x9000, v82
	s_nop 1
	v_addc_co_u32_e32 v3, vcc, 0, v83, vcc
	global_store_dword v[2:3], v4, off offset:192
.LBB0_592:
	s_or_b64 exec, exec, s[6:7]
	v_rcp_f32_e32 v2, v76
	s_nop 0
	v_mul_f32_e32 v3, v40, v2
	s_nop 1
	v_mov_b32_dpp v4, v3 quad_perm:[1,0,3,2] row_mask:0xf bank_mask:0xf
	s_and_saveexec_b64 s[6:7], s[40:41]
	s_cbranch_execz .LBB0_594
	v_cvt_pk_bf16_f32 v3, v3, v4
	v_add_co_u32_e32 v4, vcc, 0xa000, v82
	s_nop 1
	v_addc_co_u32_e32 v5, vcc, 0, v83, vcc
	global_store_dword v[4:5], v3, off
.LBB0_594:
	s_or_b64 exec, exec, s[6:7]
	v_mul_f32_e32 v3, v56, v2
	s_nop 1
	v_mov_b32_dpp v4, v3 quad_perm:[1,0,3,2] row_mask:0xf bank_mask:0xf
	s_and_saveexec_b64 s[6:7], s[40:41]
	s_cbranch_execz .LBB0_596
	v_cvt_pk_bf16_f32 v3, v3, v4
	v_add_co_u32_e32 v4, vcc, 0xa000, v82
	s_nop 1
	v_addc_co_u32_e32 v5, vcc, 0, v83, vcc
	global_store_dword v[4:5], v3, off offset:64
.LBB0_596:
	s_or_b64 exec, exec, s[6:7]
	v_mul_f32_e32 v3, v24, v2
	s_nop 1
	v_mov_b32_dpp v4, v3 quad_perm:[1,0,3,2] row_mask:0xf bank_mask:0xf
	s_and_saveexec_b64 s[6:7], s[40:41]
	s_cbranch_execz .LBB0_598
	v_cvt_pk_bf16_f32 v3, v3, v4
	v_add_co_u32_e32 v4, vcc, 0xa000, v82
	s_nop 1
	v_addc_co_u32_e32 v5, vcc, 0, v83, vcc
	global_store_dword v[4:5], v3, off offset:128
.LBB0_598:
	s_or_b64 exec, exec, s[6:7]
	v_mul_f32_e32 v2, v8, v2
	s_nop 1
	v_mov_b32_dpp v3, v2 quad_perm:[1,0,3,2] row_mask:0xf bank_mask:0xf
	s_and_saveexec_b64 s[6:7], s[40:41]
	s_cbranch_execz .LBB0_600
	v_cvt_pk_bf16_f32 v4, v2, v3
	v_add_co_u32_e32 v2, vcc, 0xa000, v82
	s_nop 1
	v_addc_co_u32_e32 v3, vcc, 0, v83, vcc
	global_store_dword v[2:3], v4, off offset:192
.LBB0_600:
	s_or_b64 exec, exec, s[6:7]
	v_rcp_f32_e32 v2, v77
	s_nop 0
	v_mul_f32_e32 v3, v41, v2
	s_nop 1
	v_mov_b32_dpp v4, v3 quad_perm:[1,0,3,2] row_mask:0xf bank_mask:0xf
	s_and_saveexec_b64 s[6:7], s[40:41]
	s_cbranch_execz .LBB0_602
	v_cvt_pk_bf16_f32 v3, v3, v4
	v_add_co_u32_e32 v4, vcc, 0xb000, v82
	s_nop 1
	v_addc_co_u32_e32 v5, vcc, 0, v83, vcc
	global_store_dword v[4:5], v3, off
.LBB0_602:
	s_or_b64 exec, exec, s[6:7]
	v_mul_f32_e32 v3, v57, v2
	s_nop 1
	v_mov_b32_dpp v4, v3 quad_perm:[1,0,3,2] row_mask:0xf bank_mask:0xf
	s_and_saveexec_b64 s[6:7], s[40:41]
	s_cbranch_execz .LBB0_604
	v_cvt_pk_bf16_f32 v3, v3, v4
	v_add_co_u32_e32 v4, vcc, 0xb000, v82
	s_nop 1
	v_addc_co_u32_e32 v5, vcc, 0, v83, vcc
	global_store_dword v[4:5], v3, off offset:64
.LBB0_604:
	s_or_b64 exec, exec, s[6:7]
	v_mul_f32_e32 v3, v25, v2
	s_nop 1
	v_mov_b32_dpp v4, v3 quad_perm:[1,0,3,2] row_mask:0xf bank_mask:0xf
	s_and_saveexec_b64 s[6:7], s[40:41]
	s_cbranch_execz .LBB0_606
	v_cvt_pk_bf16_f32 v3, v3, v4
	v_add_co_u32_e32 v4, vcc, 0xb000, v82
	s_nop 1
	v_addc_co_u32_e32 v5, vcc, 0, v83, vcc
	global_store_dword v[4:5], v3, off offset:128
.LBB0_606:
	s_or_b64 exec, exec, s[6:7]
	v_mul_f32_e32 v2, v9, v2
	s_nop 1
	v_mov_b32_dpp v3, v2 quad_perm:[1,0,3,2] row_mask:0xf bank_mask:0xf
	s_and_saveexec_b64 s[6:7], s[40:41]
	s_cbranch_execz .LBB0_608
	v_cvt_pk_bf16_f32 v4, v2, v3
	v_add_co_u32_e32 v2, vcc, 0xb000, v82
	s_nop 1
	v_addc_co_u32_e32 v3, vcc, 0, v83, vcc
	global_store_dword v[2:3], v4, off offset:192
.LBB0_608:
	s_or_b64 exec, exec, s[6:7]
	v_rcp_f32_e32 v2, v70
	s_nop 0
	v_mul_f32_e32 v3, v42, v2
	s_nop 1
	v_mov_b32_dpp v4, v3 quad_perm:[1,0,3,2] row_mask:0xf bank_mask:0xf
	s_and_saveexec_b64 s[6:7], s[40:41]
	s_cbranch_execz .LBB0_610
	v_cvt_pk_bf16_f32 v3, v3, v4
	v_add_co_u32_e32 v4, vcc, 0x10000, v82
	s_nop 1
	v_addc_co_u32_e32 v5, vcc, 0, v83, vcc
	global_store_dword v[4:5], v3, off
.LBB0_610:
	s_or_b64 exec, exec, s[6:7]
	v_mul_f32_e32 v3, v58, v2
	s_nop 1
	v_mov_b32_dpp v4, v3 quad_perm:[1,0,3,2] row_mask:0xf bank_mask:0xf
	s_and_saveexec_b64 s[6:7], s[40:41]
	s_cbranch_execz .LBB0_612
	v_cvt_pk_bf16_f32 v3, v3, v4
	v_add_co_u32_e32 v4, vcc, 0x10000, v82
	s_nop 1
	v_addc_co_u32_e32 v5, vcc, 0, v83, vcc
	global_store_dword v[4:5], v3, off offset:64
.LBB0_612:
	s_or_b64 exec, exec, s[6:7]
	v_mul_f32_e32 v3, v26, v2
	s_nop 1
	v_mov_b32_dpp v4, v3 quad_perm:[1,0,3,2] row_mask:0xf bank_mask:0xf
	s_and_saveexec_b64 s[6:7], s[40:41]
	s_cbranch_execz .LBB0_614
	v_cvt_pk_bf16_f32 v3, v3, v4
	v_add_co_u32_e32 v4, vcc, 0x10000, v82
	s_nop 1
	v_addc_co_u32_e32 v5, vcc, 0, v83, vcc
	global_store_dword v[4:5], v3, off offset:128
.LBB0_614:
	s_or_b64 exec, exec, s[6:7]
	v_mul_f32_e32 v2, v10, v2
	s_nop 1
	v_mov_b32_dpp v3, v2 quad_perm:[1,0,3,2] row_mask:0xf bank_mask:0xf
	s_and_saveexec_b64 s[6:7], s[40:41]
	s_cbranch_execz .LBB0_616
	v_cvt_pk_bf16_f32 v4, v2, v3
	v_add_co_u32_e32 v2, vcc, 0x10000, v82
	s_nop 1
	v_addc_co_u32_e32 v3, vcc, 0, v83, vcc
	global_store_dword v[2:3], v4, off offset:192
.LBB0_616:
	s_or_b64 exec, exec, s[6:7]
	v_rcp_f32_e32 v2, v71
	s_nop 0
	v_mul_f32_e32 v3, v43, v2
	s_nop 1
	v_mov_b32_dpp v4, v3 quad_perm:[1,0,3,2] row_mask:0xf bank_mask:0xf
	s_and_saveexec_b64 s[6:7], s[40:41]
	s_cbranch_execz .LBB0_618
	v_cvt_pk_bf16_f32 v3, v3, v4
	v_add_co_u32_e32 v4, vcc, 0x11000, v82
	s_nop 1
	v_addc_co_u32_e32 v5, vcc, 0, v83, vcc
	global_store_dword v[4:5], v3, off
.LBB0_618:
	s_or_b64 exec, exec, s[6:7]
	v_mul_f32_e32 v3, v59, v2
	s_nop 1
	v_mov_b32_dpp v4, v3 quad_perm:[1,0,3,2] row_mask:0xf bank_mask:0xf
	s_and_saveexec_b64 s[6:7], s[40:41]
	s_cbranch_execz .LBB0_620
	v_cvt_pk_bf16_f32 v3, v3, v4
	v_add_co_u32_e32 v4, vcc, 0x11000, v82
	s_nop 1
	v_addc_co_u32_e32 v5, vcc, 0, v83, vcc
	global_store_dword v[4:5], v3, off offset:64
.LBB0_620:
	s_or_b64 exec, exec, s[6:7]
	v_mul_f32_e32 v3, v27, v2
	s_nop 1
	v_mov_b32_dpp v4, v3 quad_perm:[1,0,3,2] row_mask:0xf bank_mask:0xf
	s_and_saveexec_b64 s[6:7], s[40:41]
	s_cbranch_execz .LBB0_622
	v_cvt_pk_bf16_f32 v3, v3, v4
	v_add_co_u32_e32 v4, vcc, 0x11000, v82
	s_nop 1
	v_addc_co_u32_e32 v5, vcc, 0, v83, vcc
	global_store_dword v[4:5], v3, off offset:128
.LBB0_622:
	s_or_b64 exec, exec, s[6:7]
	v_mul_f32_e32 v2, v11, v2
	s_nop 1
	v_mov_b32_dpp v3, v2 quad_perm:[1,0,3,2] row_mask:0xf bank_mask:0xf
	s_and_saveexec_b64 s[6:7], s[40:41]
	s_cbranch_execz .LBB0_624
	v_cvt_pk_bf16_f32 v4, v2, v3
	v_add_co_u32_e32 v2, vcc, 0x11000, v82
	s_nop 1
	v_addc_co_u32_e32 v3, vcc, 0, v83, vcc
	global_store_dword v[2:3], v4, off offset:192
.LBB0_624:
	s_or_b64 exec, exec, s[6:7]
	v_rcp_f32_e32 v2, v72
	s_nop 0
	v_mul_f32_e32 v3, v44, v2
	s_nop 1
	v_mov_b32_dpp v4, v3 quad_perm:[1,0,3,2] row_mask:0xf bank_mask:0xf
	s_and_saveexec_b64 s[6:7], s[40:41]
	s_cbranch_execz .LBB0_626
	v_cvt_pk_bf16_f32 v3, v3, v4
	v_add_co_u32_e32 v4, vcc, 0x12000, v82
	s_nop 1
	v_addc_co_u32_e32 v5, vcc, 0, v83, vcc
	global_store_dword v[4:5], v3, off
.LBB0_626:
	s_or_b64 exec, exec, s[6:7]
	v_mul_f32_e32 v3, v60, v2
	s_nop 1
	v_mov_b32_dpp v4, v3 quad_perm:[1,0,3,2] row_mask:0xf bank_mask:0xf
	s_and_saveexec_b64 s[6:7], s[40:41]
	s_cbranch_execz .LBB0_628
	v_cvt_pk_bf16_f32 v3, v3, v4
	v_add_co_u32_e32 v4, vcc, 0x12000, v82
	s_nop 1
	v_addc_co_u32_e32 v5, vcc, 0, v83, vcc
	global_store_dword v[4:5], v3, off offset:64
.LBB0_628:
	s_or_b64 exec, exec, s[6:7]
	v_mul_f32_e32 v3, v28, v2
	s_nop 1
	v_mov_b32_dpp v4, v3 quad_perm:[1,0,3,2] row_mask:0xf bank_mask:0xf
	s_and_saveexec_b64 s[6:7], s[40:41]
	s_cbranch_execz .LBB0_630
	v_cvt_pk_bf16_f32 v3, v3, v4
	v_add_co_u32_e32 v4, vcc, 0x12000, v82
	s_nop 1
	v_addc_co_u32_e32 v5, vcc, 0, v83, vcc
	global_store_dword v[4:5], v3, off offset:128
.LBB0_630:
	s_or_b64 exec, exec, s[6:7]
	v_mul_f32_e32 v2, v12, v2
	s_nop 1
	v_mov_b32_dpp v3, v2 quad_perm:[1,0,3,2] row_mask:0xf bank_mask:0xf
	s_and_saveexec_b64 s[6:7], s[40:41]
	s_cbranch_execz .LBB0_632
	v_cvt_pk_bf16_f32 v4, v2, v3
	v_add_co_u32_e32 v2, vcc, 0x12000, v82
	s_nop 1
	v_addc_co_u32_e32 v3, vcc, 0, v83, vcc
	global_store_dword v[2:3], v4, off offset:192
.LBB0_632:
	s_or_b64 exec, exec, s[6:7]
	v_rcp_f32_e32 v2, v73
	s_nop 0
	v_mul_f32_e32 v3, v45, v2
	s_nop 1
	v_mov_b32_dpp v4, v3 quad_perm:[1,0,3,2] row_mask:0xf bank_mask:0xf
	s_and_saveexec_b64 s[6:7], s[40:41]
	s_cbranch_execz .LBB0_634
	v_cvt_pk_bf16_f32 v3, v3, v4
	v_add_co_u32_e32 v4, vcc, 0x13000, v82
	s_nop 1
	v_addc_co_u32_e32 v5, vcc, 0, v83, vcc
	global_store_dword v[4:5], v3, off
.LBB0_634:
	s_or_b64 exec, exec, s[6:7]
	v_mul_f32_e32 v3, v61, v2
	s_nop 1
	v_mov_b32_dpp v4, v3 quad_perm:[1,0,3,2] row_mask:0xf bank_mask:0xf
	s_and_saveexec_b64 s[6:7], s[40:41]
	s_cbranch_execz .LBB0_636
	v_cvt_pk_bf16_f32 v3, v3, v4
	v_add_co_u32_e32 v4, vcc, 0x13000, v82
	s_nop 1
	v_addc_co_u32_e32 v5, vcc, 0, v83, vcc
	global_store_dword v[4:5], v3, off offset:64
.LBB0_636:
	s_or_b64 exec, exec, s[6:7]
	v_mul_f32_e32 v3, v29, v2
	s_nop 1
	v_mov_b32_dpp v4, v3 quad_perm:[1,0,3,2] row_mask:0xf bank_mask:0xf
	s_and_saveexec_b64 s[6:7], s[40:41]
	s_cbranch_execz .LBB0_638
	v_cvt_pk_bf16_f32 v3, v3, v4
	v_add_co_u32_e32 v4, vcc, 0x13000, v82
	s_nop 1
	v_addc_co_u32_e32 v5, vcc, 0, v83, vcc
	global_store_dword v[4:5], v3, off offset:128
.LBB0_638:
	s_or_b64 exec, exec, s[6:7]
	v_mul_f32_e32 v2, v13, v2
	s_nop 1
	v_mov_b32_dpp v3, v2 quad_perm:[1,0,3,2] row_mask:0xf bank_mask:0xf
	s_and_saveexec_b64 s[6:7], s[40:41]
	s_cbranch_execz .LBB0_640
	v_cvt_pk_bf16_f32 v4, v2, v3
	v_add_co_u32_e32 v2, vcc, 0x13000, v82
	s_nop 1
	v_addc_co_u32_e32 v3, vcc, 0, v83, vcc
	global_store_dword v[2:3], v4, off offset:192
.LBB0_640:
	s_or_b64 exec, exec, s[6:7]
	v_rcp_f32_e32 v2, v66
	s_nop 0
	v_mul_f32_e32 v3, v46, v2
	s_nop 1
	v_mov_b32_dpp v4, v3 quad_perm:[1,0,3,2] row_mask:0xf bank_mask:0xf
	s_and_saveexec_b64 s[6:7], s[40:41]
	s_cbranch_execz .LBB0_642
	v_cvt_pk_bf16_f32 v3, v3, v4
	v_add_co_u32_e32 v4, vcc, 0x18000, v82
	s_nop 1
	v_addc_co_u32_e32 v5, vcc, 0, v83, vcc
	global_store_dword v[4:5], v3, off
.LBB0_642:
	s_or_b64 exec, exec, s[6:7]
	v_mul_f32_e32 v3, v62, v2
	s_nop 1
	v_mov_b32_dpp v4, v3 quad_perm:[1,0,3,2] row_mask:0xf bank_mask:0xf
	s_and_saveexec_b64 s[6:7], s[40:41]
	s_cbranch_execz .LBB0_644
	v_cvt_pk_bf16_f32 v3, v3, v4
	v_add_co_u32_e32 v4, vcc, 0x18000, v82
	s_nop 1
	v_addc_co_u32_e32 v5, vcc, 0, v83, vcc
	global_store_dword v[4:5], v3, off offset:64
.LBB0_644:
	s_or_b64 exec, exec, s[6:7]
	v_mul_f32_e32 v3, v30, v2
	s_nop 1
	v_mov_b32_dpp v4, v3 quad_perm:[1,0,3,2] row_mask:0xf bank_mask:0xf
	s_and_saveexec_b64 s[6:7], s[40:41]
	s_cbranch_execz .LBB0_646
	v_cvt_pk_bf16_f32 v3, v3, v4
	v_add_co_u32_e32 v4, vcc, 0x18000, v82
	s_nop 1
	v_addc_co_u32_e32 v5, vcc, 0, v83, vcc
	global_store_dword v[4:5], v3, off offset:128
.LBB0_646:
	s_or_b64 exec, exec, s[6:7]
	v_mul_f32_e32 v2, v14, v2
	s_nop 1
	v_mov_b32_dpp v3, v2 quad_perm:[1,0,3,2] row_mask:0xf bank_mask:0xf
	s_and_saveexec_b64 s[6:7], s[40:41]
	s_cbranch_execz .LBB0_648
	v_cvt_pk_bf16_f32 v4, v2, v3
	v_add_co_u32_e32 v2, vcc, 0x18000, v82
	s_nop 1
	v_addc_co_u32_e32 v3, vcc, 0, v83, vcc
	global_store_dword v[2:3], v4, off offset:192
.LBB0_648:
	s_or_b64 exec, exec, s[6:7]
	v_rcp_f32_e32 v2, v67
	s_nop 0
	v_mul_f32_e32 v3, v47, v2
	s_nop 1
	v_mov_b32_dpp v4, v3 quad_perm:[1,0,3,2] row_mask:0xf bank_mask:0xf
	s_and_saveexec_b64 s[6:7], s[40:41]
	s_cbranch_execz .LBB0_650
	v_cvt_pk_bf16_f32 v3, v3, v4
	v_add_co_u32_e32 v4, vcc, 0x19000, v82
	s_nop 1
	v_addc_co_u32_e32 v5, vcc, 0, v83, vcc
	global_store_dword v[4:5], v3, off
.LBB0_650:
	s_or_b64 exec, exec, s[6:7]
	v_mul_f32_e32 v3, v63, v2
	s_nop 1
	v_mov_b32_dpp v4, v3 quad_perm:[1,0,3,2] row_mask:0xf bank_mask:0xf
	s_and_saveexec_b64 s[6:7], s[40:41]
	s_cbranch_execz .LBB0_652
	v_cvt_pk_bf16_f32 v3, v3, v4
	v_add_co_u32_e32 v4, vcc, 0x19000, v82
	s_nop 1
	v_addc_co_u32_e32 v5, vcc, 0, v83, vcc
	global_store_dword v[4:5], v3, off offset:64
.LBB0_652:
	s_or_b64 exec, exec, s[6:7]
	v_mul_f32_e32 v3, v31, v2
	s_nop 1
	v_mov_b32_dpp v4, v3 quad_perm:[1,0,3,2] row_mask:0xf bank_mask:0xf
	s_and_saveexec_b64 s[6:7], s[40:41]
	s_cbranch_execz .LBB0_654
	v_cvt_pk_bf16_f32 v3, v3, v4
	v_add_co_u32_e32 v4, vcc, 0x19000, v82
	s_nop 1
	v_addc_co_u32_e32 v5, vcc, 0, v83, vcc
	global_store_dword v[4:5], v3, off offset:128
.LBB0_654:
	s_or_b64 exec, exec, s[6:7]
	v_mul_f32_e32 v2, v15, v2
	s_nop 1
	v_mov_b32_dpp v3, v2 quad_perm:[1,0,3,2] row_mask:0xf bank_mask:0xf
	s_and_saveexec_b64 s[6:7], s[40:41]
	s_cbranch_execz .LBB0_656
	v_cvt_pk_bf16_f32 v4, v2, v3
	v_add_co_u32_e32 v2, vcc, 0x19000, v82
	s_nop 1
	v_addc_co_u32_e32 v3, vcc, 0, v83, vcc
	global_store_dword v[2:3], v4, off offset:192
.LBB0_656:
	s_or_b64 exec, exec, s[6:7]
	v_rcp_f32_e32 v2, v68
	s_nop 0
	v_mul_f32_e32 v3, v48, v2
	s_nop 1
	v_mov_b32_dpp v4, v3 quad_perm:[1,0,3,2] row_mask:0xf bank_mask:0xf
	s_and_saveexec_b64 s[6:7], s[40:41]
	s_cbranch_execz .LBB0_658
	v_cvt_pk_bf16_f32 v3, v3, v4
	v_add_co_u32_e32 v4, vcc, 0x1a000, v82
	s_nop 1
	v_addc_co_u32_e32 v5, vcc, 0, v83, vcc
	global_store_dword v[4:5], v3, off
.LBB0_658:
	s_or_b64 exec, exec, s[6:7]
	v_mul_f32_e32 v3, v64, v2
	s_nop 1
	v_mov_b32_dpp v4, v3 quad_perm:[1,0,3,2] row_mask:0xf bank_mask:0xf
	s_and_saveexec_b64 s[6:7], s[40:41]
	s_cbranch_execz .LBB0_660
	v_cvt_pk_bf16_f32 v3, v3, v4
	v_add_co_u32_e32 v4, vcc, 0x1a000, v82
	s_nop 1
	v_addc_co_u32_e32 v5, vcc, 0, v83, vcc
	global_store_dword v[4:5], v3, off offset:64
.LBB0_660:
	s_or_b64 exec, exec, s[6:7]
	v_mul_f32_e32 v3, v32, v2
	s_nop 1
	v_mov_b32_dpp v4, v3 quad_perm:[1,0,3,2] row_mask:0xf bank_mask:0xf
	s_and_saveexec_b64 s[6:7], s[40:41]
	s_cbranch_execz .LBB0_662
	v_cvt_pk_bf16_f32 v3, v3, v4
	v_add_co_u32_e32 v4, vcc, 0x1a000, v82
	s_nop 1
	v_addc_co_u32_e32 v5, vcc, 0, v83, vcc
	global_store_dword v[4:5], v3, off offset:128
.LBB0_662:
	s_or_b64 exec, exec, s[6:7]
	v_mul_f32_e32 v2, v16, v2
	s_nop 1
	v_mov_b32_dpp v3, v2 quad_perm:[1,0,3,2] row_mask:0xf bank_mask:0xf
	s_and_saveexec_b64 s[6:7], s[40:41]
	s_cbranch_execz .LBB0_664
	v_cvt_pk_bf16_f32 v4, v2, v3
	v_add_co_u32_e32 v2, vcc, 0x1a000, v82
	s_nop 1
	v_addc_co_u32_e32 v3, vcc, 0, v83, vcc
	global_store_dword v[2:3], v4, off offset:192
.LBB0_664:
	s_or_b64 exec, exec, s[6:7]
	v_rcp_f32_e32 v2, v69
	s_nop 0
	v_mul_f32_e32 v3, v49, v2
	s_nop 1
	v_mov_b32_dpp v4, v3 quad_perm:[1,0,3,2] row_mask:0xf bank_mask:0xf
	s_and_saveexec_b64 s[6:7], s[40:41]
	s_cbranch_execz .LBB0_666
	v_cvt_pk_bf16_f32 v3, v3, v4
	v_add_co_u32_e32 v4, vcc, 0x1b000, v82
	s_nop 1
	v_addc_co_u32_e32 v5, vcc, 0, v83, vcc
	global_store_dword v[4:5], v3, off
.LBB0_666:
	s_or_b64 exec, exec, s[6:7]
	v_mul_f32_e32 v3, v65, v2
	s_nop 1
	v_mov_b32_dpp v4, v3 quad_perm:[1,0,3,2] row_mask:0xf bank_mask:0xf
	s_and_saveexec_b64 s[6:7], s[40:41]
	s_cbranch_execz .LBB0_668
	v_cvt_pk_bf16_f32 v3, v3, v4
	v_add_co_u32_e32 v4, vcc, 0x1b000, v82
	s_nop 1
	v_addc_co_u32_e32 v5, vcc, 0, v83, vcc
	global_store_dword v[4:5], v3, off offset:64
.LBB0_668:
	s_or_b64 exec, exec, s[6:7]
	v_mul_f32_e32 v3, v33, v2
	s_nop 1
	v_mov_b32_dpp v4, v3 quad_perm:[1,0,3,2] row_mask:0xf bank_mask:0xf
	s_and_saveexec_b64 s[6:7], s[40:41]
	s_cbranch_execz .LBB0_670
	v_cvt_pk_bf16_f32 v3, v3, v4
	v_add_co_u32_e32 v4, vcc, 0x1b000, v82
	s_nop 1
	v_addc_co_u32_e32 v5, vcc, 0, v83, vcc
	global_store_dword v[4:5], v3, off offset:128
.LBB0_670:
	s_mov_b32 s42, s28
	s_or_b64 exec, exec, s[6:7]
	v_mul_f32_e32 v2, v17, v2
	s_nop 1
	v_mov_b32_dpp v3, v2 quad_perm:[1,0,3,2] row_mask:0xf bank_mask:0xf
	s_and_saveexec_b64 s[6:7], s[40:41]
	s_cbranch_execz .LBB0_672
	v_cvt_pk_bf16_f32 v4, v2, v3
	v_add_co_u32_e32 v2, vcc, 0x1b000, v82
	s_nop 1
	v_addc_co_u32_e32 v3, vcc, 0, v83, vcc
	global_store_dword v[2:3], v4, off offset:192
.LBB0_672:
	s_or_b64 exec, exec, s[6:7]
	v_mov_b32_e32 v163, v0
	s_barrier
	s_add_i32 s7, s31, 0x100
	v_readfirstlane_b32 s6, v163
	s_ashr_i32 s11, s6, 1
	s_andn2_b32 s11, s11, 31
	v_and_b32_e32 v173, 31, v163
	s_lshr_b32 s28, s7, 6
	s_lshl_b32 s7, s11, 2
	v_ashrrev_i32_e32 v83, 4, v163
	s_add_i32 s7, s7, 0
	v_lshlrev_b32_e32 v82, 2, v173
	v_add_u32_e32 v181, 32, v83
	v_add_u32_e32 v2, s7, v82
	v_and_b32_e32 v3, 0xfffff0, v83
	v_lshlrev_b32_e32 v4, 1, v83
	v_and_b32_e32 v6, 0xfffff0, v181
	v_lshlrev_b32_e32 v7, 1, v181
	v_add_u32_e32 v183, 0x10c00, v2
	v_lshlrev_b32_e32 v2, 3, v163
	v_and_or_b32 v3, v4, 8, v3
	v_and_or_b32 v6, v7, 8, v6
	v_and_b32_e32 v162, 0x78, v2
	v_lshrrev_b32_e32 v4, 1, v83
	v_lshrrev_b32_e32 v3, 1, v3
	v_bfe_u32 v2, v2, 5, 2
	v_and_b32_e32 v5, 3, v83
	v_lshrrev_b32_e32 v6, 1, v6
	s_and_b32 s6, s6, 0x3fffffc0
	v_or_b32_e32 v3, v3, v2
	v_and_or_b32 v4, v4, 4, v5
	v_lshlrev_b32_e32 v202, 1, v162
	v_or_b32_e32 v2, v6, v2
	s_lshl_b32 s6, s6, 2
	v_lshlrev_b32_e32 v3, 9, v3
	v_lshlrev_b32_e32 v4, 6, v4
	v_and_b32_e32 v5, 48, v202
	v_lshlrev_b32_e32 v2, 9, v2
	v_and_b32_e32 v174, 63, v163
	s_add_i32 s6, s6, 0
	v_or3_b32 v3, v3, v4, v5
	v_or3_b32 v2, v2, v4, v5
	v_lshlrev_b32_e32 v4, 8, v83
	v_and_b32_e32 v5, 0x70, v163
	v_lshlrev_b32_e32 v6, 4, v163
	s_add_i32 s10, s11, s31
	s_add_i32 s6, s6, 0x10000
	v_bitop3_b32 v84, v202, v4, v5 bitop3:0xde
	v_lshlrev_b32_e32 v4, 3, v174
	v_and_b32_e32 v5, 0xc0, v6
	v_lshlrev_b32_e32 v7, 1, v163
	v_and_or_b32 v5, v4, 24, v5
	v_and_b32_e32 v7, 32, v7
	v_and_b32_e32 v4, 0x100, v4
	s_cmp_lg_u32 0, -1
	v_bfe_u32 v172, v163, 5, 1
	v_or3_b32 v4, v5, v7, v4
	s_cselect_b32 s7, 0, 0
	s_mov_b32 s29, 2
	v_lshlrev_b32_e32 v180, 2, v172
	v_add_u32_e32 v175, s7, v4
	v_add_u32_e32 v186, 0, v3
	v_add_u32_e32 v188, 0, v2
	ds_write_b128 v186, v[134:137]
	ds_write_b128 v188, v[130:133]
	v_add_u32_e32 v7, 64, v83
	v_mov_b64_e32 v[2:3], s[18:19]
	v_add_u32_e32 v8, 0x60, v83
	v_mad_i64_i32 v[4:5], s[8:9], v7, s3, v[2:3]
	v_mad_i64_i32 v[2:3], s[8:9], v8, s3, v[2:3]
	v_lshl_add_u64 v[4:5], v[4:5], 0, v[202:203]
	v_lshl_add_u64 v[2:3], v[2:3], 0, v[202:203]
	global_load_dwordx4 v[50:53], v[4:5], off
	global_load_dwordx4 v[54:57], v[2:3], off
	v_mov_b64_e32 v[2:3], s[38:39]
	v_mad_i64_i32 v[4:5], s[8:9], v7, s3, v[2:3]
	v_lshl_add_u64 v[4:5], v[4:5], 0, v[202:203]
	v_mad_i64_i32 v[2:3], s[8:9], v8, s3, v[2:3]
	v_lshl_add_u64 v[2:3], v[2:3], 0, v[202:203]
	global_load_dwordx4 v[58:61], v[4:5], off
	global_load_dwordx4 v[62:65], v[2:3], off
	v_lshlrev_b32_e32 v85, 4, v172
	v_and_b32_e32 v71, 0x70, v6
	v_lshlrev_b32_e32 v70, 8, v173
	v_xad_u32 v2, v85, v71, 0
	v_add_u32_e32 v182, v2, v70
	ds_read_b128 v[2:5], v182 offset:32768
	ds_read_b32 v86, v183
	v_or_b32_e32 v6, 32, v85
	s_waitcnt vmcnt(11) lgkmcnt(1)
	v_mfma_f32_32x32x16_bf16 v[34:49], v[2:5], v[126:129], 0
	ds_read_b128 v[2:5], v182 offset:40960
	v_xad_u32 v6, v6, v71, 0
	v_add_u32_e32 v187, v6, v70
	ds_read_b128 v[6:9], v182 offset:32896
	v_or_b32_e32 v14, 64, v85
	v_xad_u32 v14, v14, v71, 0
	v_add_u32_e32 v185, v14, v70
	s_waitcnt lgkmcnt(1)
	v_mfma_f32_32x32x16_bf16 v[18:33], v[2:5], v[126:129], 0
	ds_read_b128 v[2:5], v187 offset:32768
	ds_read_b128 v[10:13], v182 offset:41088
	ds_read_b128 v[14:17], v187 offset:32896
	v_or_b32_e32 v72, 0x60, v85
	v_xad_u32 v71, v72, v71, 0
	v_add_u32_e32 v184, v71, v70
	v_add_u32_e32 v177, s6, v82
	v_add_u32_e32 v176, s6, v85
	s_waitcnt vmcnt(10) lgkmcnt(2)
	v_mfma_f32_32x32x16_bf16 v[34:49], v[2:5], v[122:125], v[34:49]
	ds_read_b128 v[2:5], v187 offset:40960
	s_mov_b32 s12, s13
	s_mov_b32 s14, s13
	s_mov_b32 s15, s13
	s_mov_b32 s16, s13
	s_mov_b32 s17, s13
	s_mov_b32 s18, s13
	s_waitcnt lgkmcnt(0)
	v_mfma_f32_32x32x16_bf16 v[18:33], v[2:5], v[122:125], v[18:33]
	ds_read_b128 v[2:5], v185 offset:32768
	ds_read_b128 v[66:69], v187 offset:41088
	ds_read_b128 v[70:73], v185 offset:32896
	s_mov_b32 s19, s13
	s_mov_b32 s20, s13
	s_mov_b32 s21, s13
	s_mov_b32 s22, s13
	s_mov_b32 s23, s13
	s_waitcnt vmcnt(9) lgkmcnt(2)
	v_mfma_f32_32x32x16_bf16 v[34:49], v[2:5], v[118:121], v[34:49]
	ds_read_b128 v[2:5], v185 offset:40960
	s_mov_b32 s24, s13
	s_mov_b32 s25, s13
	s_mov_b32 s26, s13
	s_mov_b32 s27, s13
	v_add_u32_e32 v178, 0, v84
	v_cmp_gt_u32_e64 s[40:41], 32, v174
	s_waitcnt lgkmcnt(0)
	v_mfma_f32_32x32x16_bf16 v[18:33], v[2:5], v[118:121], v[18:33]
	ds_read_b128 v[2:5], v184 offset:32768
	ds_read_b128 v[74:77], v185 offset:41088
	v_mov_b32_e32 v179, 0
	s_waitcnt vmcnt(8) lgkmcnt(1)
	v_mfma_f32_32x32x16_bf16 v[34:49], v[2:5], v[114:117], v[34:49]
	ds_read_b128 v[2:5], v184 offset:40960
	ds_read_b128 v[78:81], v184 offset:32896
	s_waitcnt vmcnt(7)
	v_mfma_f32_32x32x16_bf16 v[34:49], v[6:9], v[110:113], v[34:49]
	s_waitcnt lgkmcnt(1)
	v_mfma_f32_32x32x16_bf16 v[18:33], v[2:5], v[114:117], v[18:33]
	s_waitcnt vmcnt(6)
	v_mfma_f32_32x32x16_bf16 v[34:49], v[14:17], v[106:109], v[34:49]
	v_mfma_f32_32x32x16_bf16 v[18:33], v[10:13], v[110:113], v[18:33]
	v_mov_b64_e32 v[2:3], s[12:13]
	v_mov_b64_e32 v[16:17], s[26:27]
	v_mov_b64_e32 v[4:5], s[14:15]
	v_mov_b64_e32 v[6:7], s[16:17]
	v_mov_b64_e32 v[8:9], s[18:19]
	v_mov_b64_e32 v[10:11], s[20:21]
	v_mov_b64_e32 v[12:13], s[22:23]
	s_waitcnt vmcnt(5)
	v_mfma_f32_32x32x16_bf16 v[34:49], v[70:73], v[102:105], v[34:49]
	ds_read_b128 v[70:73], v184 offset:41088
	s_waitcnt vmcnt(0)
	v_mov_b64_e32 v[14:15], s[24:25]
	s_waitcnt vmcnt(3)
	ds_write_b128 v186, v[50:53] offset:16384
	s_waitcnt vmcnt(2)
	ds_write_b128 v188, v[54:57] offset:16384
	s_waitcnt vmcnt(1)
	ds_write_b128 v178, v[58:61] offset:49152
	s_waitcnt vmcnt(0)
	ds_write_b128 v178, v[62:65] offset:57344
	v_mov_b64_e32 v[64:65], v[16:17]
	s_movk_i32 s12, 0xbf
	v_mfma_f32_32x32x16_bf16 v[18:33], v[66:69], v[106:109], v[18:33]
	v_mov_b64_e32 v[62:63], v[14:15]
	v_mov_b64_e32 v[60:61], v[12:13]
	v_mov_b64_e32 v[58:59], v[10:11]
	v_mov_b64_e32 v[56:57], v[8:9]
	v_mov_b64_e32 v[54:55], v[6:7]
	v_mov_b64_e32 v[52:53], v[4:5]
	v_mov_b64_e32 v[50:51], v[2:3]
	s_waitcnt lgkmcnt(5)
	v_mfma_f32_32x32x16_bf16 v[34:49], v[78:81], v[98:101], v[34:49]
	v_and_b32_e32 v78, 1, v86
	v_cmp_eq_u32_e32 vcc, 0, v78
	s_waitcnt lgkmcnt(0)
	s_barrier
	s_nop 7
	v_cndmask_b32_e32 v66, v34, v233, vcc
	v_mfma_f32_32x32x16_bf16 v[18:33], v[74:77], v[102:105], v[18:33]
	v_cndmask_b32_e32 v35, v35, v233, vcc
	v_max_f32_e32 v34, v35, v35
	v_max_f32_e32 v67, v66, v66
	v_cndmask_b32_e32 v37, v37, v233, vcc
	v_cndmask_b32_e32 v36, v36, v233, vcc
	v_max_f32_e32 v34, v67, v34
	v_cndmask_b32_e32 v39, v39, v233, vcc
	v_mfma_f32_32x32x16_bf16 v[18:33], v[70:73], v[98:101], v[18:33]
	v_cndmask_b32_e32 v38, v38, v233, vcc
	v_max3_f32 v34, v34, v36, v37
	v_cndmask_b32_e32 v41, v41, v233, vcc
	v_cndmask_b32_e32 v40, v40, v233, vcc
	v_max3_f32 v34, v34, v38, v39
	v_cndmask_b32_e32 v43, v43, v233, vcc
	v_cndmask_b32_e32 v42, v42, v233, vcc
	v_max3_f32 v34, v34, v40, v41
	v_cndmask_b32_e32 v45, v45, v233, vcc
	v_cndmask_b32_e32 v44, v44, v233, vcc
	v_max3_f32 v34, v34, v42, v43
	v_cndmask_b32_e32 v47, v47, v233, vcc
	v_cndmask_b32_e32 v46, v46, v233, vcc
	v_max3_f32 v34, v34, v44, v45
	v_cndmask_b32_e32 v49, v49, v233, vcc
	v_cndmask_b32_e32 v48, v48, v233, vcc
	v_max3_f32 v34, v34, v46, v47
	v_cndmask_b32_e32 v19, v19, v233, vcc
	v_cndmask_b32_e32 v18, v18, v233, vcc
	v_max3_f32 v34, v34, v48, v49
	v_cndmask_b32_e32 v21, v21, v233, vcc
	v_cndmask_b32_e32 v20, v20, v233, vcc
	v_max3_f32 v34, v34, v18, v19
	v_cndmask_b32_e32 v23, v23, v233, vcc
	v_cndmask_b32_e32 v22, v22, v233, vcc
	v_max3_f32 v34, v34, v20, v21
	v_cndmask_b32_e32 v25, v25, v233, vcc
	v_cndmask_b32_e32 v24, v24, v233, vcc
	v_max3_f32 v34, v34, v22, v23
	v_cndmask_b32_e32 v27, v27, v233, vcc
	v_cndmask_b32_e32 v26, v26, v233, vcc
	v_max3_f32 v34, v34, v24, v25
	v_cndmask_b32_e32 v29, v29, v233, vcc
	v_cndmask_b32_e32 v28, v28, v233, vcc
	v_max3_f32 v34, v34, v26, v27
	v_cndmask_b32_e32 v31, v31, v233, vcc
	v_cndmask_b32_e32 v30, v30, v233, vcc
	v_max3_f32 v34, v34, v28, v29
	v_cndmask_b32_e32 v33, v33, v233, vcc
	v_cndmask_b32_e32 v32, v32, v233, vcc
	v_max3_f32 v34, v34, v30, v31
	v_max3_f32 v34, v34, v32, v33
	v_mov_b32_e32 v67, v34
	s_nop 1
	v_permlane32_swap_b32_e32 v34, v67
	v_max_f32_e32 v67, v67, v67
	v_max_f32_e32 v34, v34, v34
	v_max_f32_e32 v34, v34, v67
	v_add_f32_e32 v67, 0x7149f2ca, v34
	v_mul_f32_e32 v67, 0x3db504f3, v67
	v_cmp_ge_f32_e32 vcc, s35, v67
	s_cmp_eq_u64 vcc, exec
	v_max_f32_e32 v34, 0xf149f2ca, v34
	s_cselect_b64 vcc, -1, 0
	v_sub_f32_e32 v67, 0xf149f2ca, v34
	v_cndmask_b32_e32 v193, v34, v234, vcc
	v_mul_f32_e32 v67, 0x3e0293ee, v67
	v_mul_f32_e32 v34, 0xbe0293ee, v193
	v_exp_f32_e32 v67, v67
	v_fmamk_f32 v35, v35, 0x3e0293ee, v34
	s_add_i32 s6, s10, 0xffffff80
	v_pk_fma_f32 v[144:145], v[18:19], s[34:35], v[34:35] op_sel_hi:[1,0,0]
	v_add_u32_e32 v18, s6, v173
	v_mad_i64_i32 v[164:165], s[6:7], v83, s3, 0
	v_readlane_b32 s6, v248, 51
	s_add_u32 s6, s6, s42
	v_readlane_b32 s7, v248, 52
	v_cndmask_b32_e64 v189, v67, 1.0, vcc
	v_mov_b32_e32 v67, v34
	s_addc_u32 s7, 0, s7
	v_fmamk_f32 v66, v66, 0x3e0293ee, v34
	v_fmamk_f32 v36, v36, 0x3e0293ee, v34
	v_fmamk_f32 v37, v37, 0x3e0293ee, v34
	v_fmamk_f32 v38, v38, 0x3e0293ee, v34
	v_fmamk_f32 v39, v39, 0x3e0293ee, v34
	v_fmamk_f32 v40, v40, 0x3e0293ee, v34
	v_fmamk_f32 v41, v41, 0x3e0293ee, v34
	v_fmamk_f32 v42, v42, 0x3e0293ee, v34
	v_fmamk_f32 v43, v43, 0x3e0293ee, v34
	v_fmamk_f32 v44, v44, 0x3e0293ee, v34
	v_fmamk_f32 v45, v45, 0x3e0293ee, v34
	v_fmamk_f32 v46, v46, 0x3e0293ee, v34
	v_fmamk_f32 v47, v47, 0x3e0293ee, v34
	v_fmamk_f32 v48, v48, 0x3e0293ee, v34
	v_fmac_f32_e32 v67, 0x3e0293ee, v49
	v_pk_fma_f32 v[140:141], v[20:21], s[34:35], v[34:35] op_sel_hi:[1,0,0]
	v_sub_u32_e32 v190, v18, v180
	v_mov_b64_e32 v[18:19], s[6:7]
	v_and_b32_e32 v20, 15, v163
	v_exp_f32_e32 v147, v66
	v_exp_f32_e32 v148, v35
	v_exp_f32_e32 v149, v36
	v_exp_f32_e32 v171, v37
	v_exp_f32_e32 v197, v38
	v_exp_f32_e32 v199, v39
	v_exp_f32_e32 v170, v40
	v_exp_f32_e32 v198, v41
	v_exp_f32_e32 v156, v42
	v_exp_f32_e32 v158, v43
	v_exp_f32_e32 v159, v44
	v_exp_f32_e32 v168, v45
	v_exp_f32_e32 v157, v46
	v_exp_f32_e32 v160, v47
	v_exp_f32_e32 v161, v48
	v_exp_f32_e32 v169, v67
	v_mad_i64_i32 v[18:19], s[6:7], v83, s3, v[18:19]
	v_lshlrev_b32_e32 v202, 4, v20
	v_lshl_add_u64 v[18:19], v[18:19], 0, v[202:203]
	v_pk_fma_f32 v[132:133], v[32:33], s[34:35], v[34:35] op_sel_hi:[1,0,0]
	v_pk_fma_f32 v[138:139], v[30:31], s[34:35], v[34:35] op_sel_hi:[1,0,0]
	v_pk_fma_f32 v[142:143], v[28:29], s[34:35], v[34:35] op_sel_hi:[1,0,0]
	v_pk_fma_f32 v[130:131], v[26:27], s[34:35], v[34:35] op_sel_hi:[1,0,0]
	v_pk_fma_f32 v[134:135], v[24:25], s[34:35], v[34:35] op_sel_hi:[1,0,0]
	v_pk_fma_f32 v[136:137], v[22:23], s[34:35], v[34:35] op_sel_hi:[1,0,0]
	v_lshl_add_u64 v[166:167], s[4:5], 0, v[18:19]
	v_mov_b64_e32 v[48:49], v[16:17]
	v_mov_b64_e32 v[32:33], v[16:17]
	v_mov_b64_e32 v[46:47], v[14:15]
	v_mov_b64_e32 v[44:45], v[12:13]
	v_mov_b64_e32 v[42:43], v[10:11]
	v_mov_b64_e32 v[40:41], v[8:9]
	v_mov_b64_e32 v[38:39], v[6:7]
	v_mov_b64_e32 v[36:37], v[4:5]
	v_mov_b64_e32 v[34:35], v[2:3]
	v_mov_b64_e32 v[30:31], v[14:15]
	v_mov_b64_e32 v[28:29], v[12:13]
	v_mov_b64_e32 v[26:27], v[10:11]
	v_mov_b64_e32 v[24:25], v[8:9]
	v_mov_b64_e32 v[22:23], v[6:7]
	v_mov_b64_e32 v[20:21], v[4:5]
	v_mov_b64_e32 v[18:19], v[2:3]

.LBB0_709:
	v_cndmask_b32_e64 v109, v109, v193, s[42:43]
	v_mul_f32_e32 v109, 0xbe0293ee, v109
	v_fmamk_f32 v82, v82, 0x3e0293ee, v109
	v_fmamk_f32 v83, v83, 0x3e0293ee, v109
	v_fmamk_f32 v118, v95, 0x3e0293ee, v109
	v_fmamk_f32 v95, v76, 0x3e0293ee, v109
	v_exp_f32_e32 v76, v82
	v_fmamk_f32 v84, v84, 0x3e0293ee, v109
	v_fmamk_f32 v119, v96, 0x3e0293ee, v109
	v_fmamk_f32 v96, v77, 0x3e0293ee, v109
	v_exp_f32_e32 v77, v83
	v_fmamk_f32 v85, v85, 0x3e0293ee, v109
	v_fmamk_f32 v120, v97, 0x3e0293ee, v109
	v_fmamk_f32 v97, v78, 0x3e0293ee, v109
	v_exp_f32_e32 v78, v84
	v_fmamk_f32 v86, v86, 0x3e0293ee, v109
	v_fmamk_f32 v66, v66, 0x3e0293ee, v109
	v_exp_f32_e32 v82, v85
	v_fmamk_f32 v110, v87, 0x3e0293ee, v109
	v_fmamk_f32 v111, v88, 0x3e0293ee, v109
	v_fmamk_f32 v112, v89, 0x3e0293ee, v109
	v_fmamk_f32 v113, v90, 0x3e0293ee, v109
	v_fmamk_f32 v114, v91, 0x3e0293ee, v109
	v_fmamk_f32 v115, v92, 0x3e0293ee, v109
	v_fmamk_f32 v116, v93, 0x3e0293ee, v109
	v_fmamk_f32 v117, v94, 0x3e0293ee, v109
	v_fmamk_f32 v67, v67, 0x3e0293ee, v109
	v_fmamk_f32 v87, v68, 0x3e0293ee, v109
	v_fmamk_f32 v88, v69, 0x3e0293ee, v109
	v_fmamk_f32 v89, v70, 0x3e0293ee, v109
	v_fmamk_f32 v90, v71, 0x3e0293ee, v109
	v_fmamk_f32 v91, v72, 0x3e0293ee, v109
	v_fmamk_f32 v92, v73, 0x3e0293ee, v109
	v_fmamk_f32 v93, v74, 0x3e0293ee, v109
	v_fmamk_f32 v94, v75, 0x3e0293ee, v109
	v_exp_f32_e32 v83, v86
	v_fmamk_f32 v79, v79, 0x3e0293ee, v109
	v_fmamk_f32 v80, v80, 0x3e0293ee, v109
	v_fmac_f32_e32 v109, 0x3e0293ee, v81
	v_exp_f32_e32 v81, v66
	v_add_f32_e32 v66, 0, v76
	v_exp_f32_e32 v84, v110
	v_add_f32_e32 v66, v77, v66
	v_exp_f32_e32 v85, v111
	v_add_f32_e32 v66, v78, v66
	v_exp_f32_e32 v86, v112
	v_add_f32_e32 v66, v82, v66
	v_exp_f32_e32 v68, v113
	v_add_f32_e32 v66, v83, v66
	v_exp_f32_e32 v69, v114
	v_add_f32_e32 v66, v84, v66
	v_exp_f32_e32 v70, v115
	v_add_f32_e32 v66, v85, v66
	v_exp_f32_e32 v71, v116
	v_add_f32_e32 v66, v86, v66
	v_exp_f32_e32 v72, v117
	v_add_f32_e32 v66, v68, v66
	v_exp_f32_e32 v73, v118
	v_add_f32_e32 v66, v69, v66
	v_exp_f32_e32 v74, v119
	v_add_f32_e32 v66, v70, v66
	v_exp_f32_e32 v75, v120
	v_add_f32_e32 v66, v71, v66
	v_add_f32_e32 v66, v72, v66
	v_exp_f32_e32 v110, v67
	v_add_f32_e32 v66, v73, v66
	v_exp_f32_e32 v87, v87
	v_add_f32_e32 v66, v74, v66
	v_exp_f32_e32 v88, v88
	v_add_f32_e32 v66, v75, v66
	v_exp_f32_e32 v89, v89
	v_add_f32_e32 v66, v81, v66
	v_exp_f32_e32 v90, v90
	v_add_f32_e32 v66, v110, v66
	v_exp_f32_e32 v91, v91
	v_add_f32_e32 v66, v87, v66
	v_exp_f32_e32 v92, v92
	v_add_f32_e32 v66, v88, v66
	v_exp_f32_e32 v93, v93
	v_add_f32_e32 v66, v89, v66
	v_exp_f32_e32 v94, v94
	v_add_f32_e32 v66, v90, v66
	v_exp_f32_e32 v95, v95
	v_add_f32_e32 v66, v91, v66
	v_exp_f32_e32 v96, v96
	v_add_f32_e32 v66, v92, v66
	v_exp_f32_e32 v97, v97
	v_add_f32_e32 v66, v93, v66
	v_exp_f32_e32 v111, v79
	v_add_f32_e32 v66, v94, v66
	v_exp_f32_e32 v112, v80
	v_add_f32_e32 v66, v95, v66
	v_exp_f32_e32 v109, v109
	v_add_f32_e32 v66, v96, v66
	v_add_f32_e32 v66, v97, v66
	v_add_f32_e32 v66, v111, v66
	v_add_f32_e32 v66, v112, v66
	v_add_f32_e32 v66, v109, v66
	v_mov_b32_e32 v67, v66
	s_nop 1
	v_permlane32_swap_b32_e32 v66, v67
	v_cvt_pk_bf16_f32 v76, v76, v77
	v_cvt_pk_bf16_f32 v77, v78, v82
	v_cvt_pk_bf16_f32 v78, v83, v84
	v_cvt_pk_bf16_f32 v79, v85, v86
	v_cvt_pk_bf16_f32 v68, v68, v69
	v_cvt_pk_bf16_f32 v69, v70, v71
	v_cvt_pk_bf16_f32 v70, v72, v73
	v_cvt_pk_bf16_f32 v71, v74, v75
	v_cvt_pk_bf16_f32 v72, v81, v110
	v_cvt_pk_bf16_f32 v73, v87, v88
	v_cvt_pk_bf16_f32 v74, v89, v90
	v_cvt_pk_bf16_f32 v75, v91, v92
	v_cvt_pk_bf16_f32 v80, v93, v94
	v_cvt_pk_bf16_f32 v81, v95, v96
	v_cvt_pk_bf16_f32 v82, v97, v111
	v_cvt_pk_bf16_f32 v83, v112, v109
	v_permlane32_swap_b32_e32 v76, v78
	v_permlane32_swap_b32_e32 v77, v79
	v_permlane32_swap_b32_e32 v68, v70
	v_permlane32_swap_b32_e32 v69, v71
	v_permlane32_swap_b32_e32 v72, v74
	v_permlane32_swap_b32_e32 v73, v75
	v_permlane32_swap_b32_e32 v80, v82
	v_permlane32_swap_b32_e32 v81, v83
	ds_read_b64_tr_b16 v[84:85], v175 offset:0x4000
	ds_read_b64_tr_b16 v[86:87], v175 offset:0x4800
	ds_read_b64_tr_b16 v[88:89], v175 offset:0x5000
	ds_read_b64_tr_b16 v[90:91], v175 offset:0x5800
	ds_read_b64_tr_b16 v[92:93], v175 offset:0x6000
	ds_read_b64_tr_b16 v[94:95], v175 offset:0x6800
	ds_read_b64_tr_b16 v[110:111], v175 offset:0x7000
	ds_read_b64_tr_b16 v[112:113], v175 offset:0x7800
	s_waitcnt lgkmcnt(0)
	s_nop 0
	v_mfma_f32_32x32x16_bf16 v[2:17], v[76:79], v[84:87], v[2:17]
	ds_read_b64_tr_b16 v[84:85], v175 offset:0x4200
	ds_read_b64_tr_b16 v[86:87], v175 offset:0x4a00
	v_mfma_f32_32x32x16_bf16 v[2:17], v[68:71], v[88:91], v[2:17]
	ds_read_b64_tr_b16 v[88:89], v175 offset:0x5200
	ds_read_b64_tr_b16 v[90:91], v175 offset:0x5a00
	v_mfma_f32_32x32x16_bf16 v[2:17], v[72:75], v[92:95], v[2:17]
	ds_read_b64_tr_b16 v[92:93], v175 offset:0x6200
	ds_read_b64_tr_b16 v[94:95], v175 offset:0x6a00
	v_mfma_f32_32x32x16_bf16 v[2:17], v[80:83], v[110:113], v[2:17]
	ds_read_b64_tr_b16 v[110:111], v175 offset:0x7200
	ds_read_b64_tr_b16 v[112:113], v175 offset:0x7a00
	s_waitcnt lgkmcnt(0)
	v_mfma_f32_32x32x16_bf16 v[50:65], v[76:79], v[84:87], v[50:65]
	ds_read_b64_tr_b16 v[84:85], v175 offset:0x4400
	ds_read_b64_tr_b16 v[86:87], v175 offset:0x4c00
	v_mfma_f32_32x32x16_bf16 v[50:65], v[68:71], v[88:91], v[50:65]
	ds_read_b64_tr_b16 v[88:89], v175 offset:0x5400
	ds_read_b64_tr_b16 v[90:91], v175 offset:0x5c00
	v_mfma_f32_32x32x16_bf16 v[50:65], v[72:75], v[92:95], v[50:65]
	ds_read_b64_tr_b16 v[92:93], v175 offset:0x6400
	ds_read_b64_tr_b16 v[94:95], v175 offset:0x6c00
	v_mfma_f32_32x32x16_bf16 v[50:65], v[80:83], v[110:113], v[50:65]
	ds_read_b64_tr_b16 v[110:111], v175 offset:0x7400
	ds_read_b64_tr_b16 v[112:113], v175 offset:0x7c00
	s_waitcnt lgkmcnt(0)
	v_mfma_f32_32x32x16_bf16 v[34:49], v[76:79], v[84:87], v[34:49]
	ds_read_b64_tr_b16 v[84:85], v175 offset:0x4600
	ds_read_b64_tr_b16 v[86:87], v175 offset:0x4e00
	v_mfma_f32_32x32x16_bf16 v[34:49], v[68:71], v[88:91], v[34:49]
	ds_read_b64_tr_b16 v[88:89], v175 offset:0x5600
	ds_read_b64_tr_b16 v[90:91], v175 offset:0x5e00
	v_mfma_f32_32x32x16_bf16 v[34:49], v[72:75], v[92:95], v[34:49]
	ds_read_b64_tr_b16 v[92:93], v175 offset:0x6600
	ds_read_b64_tr_b16 v[94:95], v175 offset:0x6e00
	v_mfma_f32_32x32x16_bf16 v[34:49], v[80:83], v[110:113], v[34:49]
	ds_read_b64_tr_b16 v[110:111], v175 offset:0x7600
	ds_read_b64_tr_b16 v[112:113], v175 offset:0x7e00
	s_waitcnt lgkmcnt(0)
	v_mfma_f32_32x32x16_bf16 v[18:33], v[76:79], v[84:87], v[18:33]
	v_mfma_f32_32x32x16_bf16 v[18:33], v[68:71], v[88:91], v[18:33]
	v_mfma_f32_32x32x16_bf16 v[18:33], v[72:75], v[92:95], v[18:33]
	v_mfma_f32_32x32x16_bf16 v[18:33], v[80:83], v[110:113], v[18:33]
	s_waitcnt vmcnt(8)
	s_waitcnt vmcnt(1)
	ds_write_b128 v178, v[98:101] offset:32768
	s_waitcnt vmcnt(0)
	ds_write_b128 v178, v[102:105] offset:40960
	s_and_saveexec_b64 s[4:5], s[40:41]
	v_add_f32_e32 v68, v106, v107
	v_fmac_f32_e32 v68, v179, v146
	v_add_f32_e32 v66, v66, v67
	v_fmac_f32_e32 v66, v68, v108
	ds_write_b32 v177, v66
	s_or_b64 exec, exec, s[4:5]
	s_waitcnt lgkmcnt(0)
	ds_read_b128 v[78:81], v176
	ds_read_b128 v[74:77], v176 offset:32
	s_ashr_i32 s11, s10, 31
	ds_read_b128 v[70:73], v176 offset:64
	ds_read_b128 v[66:69], v176 offset:96
	s_lshl_b64 s[4:5], s[10:11], 12
	s_waitcnt lgkmcnt(3)
	v_rcp_f32_e32 v84, v78
	v_lshlrev_b32_e32 v78, 2, v174
	v_xor_b32_e32 v78, 4, v78
	v_readlane_b32 s6, v248, 53
	v_mul_f32_e32 v2, v2, v84
	s_waitcnt lgkmcnt(0)
	s_nop 1
	v_mov_b32_dpp v85, v2 quad_perm:[1,0,3,2] row_mask:0xf bank_mask:0xf
	s_add_u32 s4, s6, s4
	v_readlane_b32 s6, v248, 54
	s_addc_u32 s5, s6, s5
	v_and_b32_e32 v82, 1, v163
	v_lshlrev_b32_e32 v202, 1, v173
	v_cmp_eq_u32_e64 s[40:41], 0, v82
	v_lshl_add_u64 v[82:83], s[4:5], 0, v[202:203]
	v_lshlrev_b32_e32 v202, 14, v172
	v_lshl_add_u64 v[82:83], v[82:83], 0, v[202:203]
	s_and_saveexec_b64 s[4:5], s[40:41]
	s_cbranch_execz .LBB0_713
	v_cvt_pk_bf16_f32 v2, v2, v85
	global_store_dword v[82:83], v2, off
.LBB0_713:
	s_or_b64 exec, exec, s[4:5]
	v_mul_f32_e32 v2, v50, v84
	s_nop 1
	v_mov_b32_dpp v50, v2 quad_perm:[1,0,3,2] row_mask:0xf bank_mask:0xf
	s_and_saveexec_b64 s[4:5], s[40:41]
	s_cbranch_execz .LBB0_715
	v_cvt_pk_bf16_f32 v2, v2, v50
	global_store_dword v[82:83], v2, off offset:64
.LBB0_715:
	s_or_b64 exec, exec, s[4:5]
	v_mul_f32_e32 v2, v34, v84
	s_nop 1
	v_mov_b32_dpp v34, v2 quad_perm:[1,0,3,2] row_mask:0xf bank_mask:0xf
	s_and_saveexec_b64 s[4:5], s[40:41]
	s_cbranch_execz .LBB0_717
	v_cvt_pk_bf16_f32 v2, v2, v34
	global_store_dword v[82:83], v2, off offset:128
.LBB0_717:
	s_or_b64 exec, exec, s[4:5]
	v_mul_f32_e32 v2, v18, v84
	s_nop 1
	v_mov_b32_dpp v18, v2 quad_perm:[1,0,3,2] row_mask:0xf bank_mask:0xf
	s_and_saveexec_b64 s[4:5], s[40:41]
	s_cbranch_execz .LBB0_719
	v_cvt_pk_bf16_f32 v2, v2, v18
	global_store_dword v[82:83], v2, off offset:192
.LBB0_719:
	s_or_b64 exec, exec, s[4:5]
	v_rcp_f32_e32 v2, v79
	s_nop 0
	v_mul_f32_e32 v3, v3, v2
	s_nop 1
	v_mov_b32_dpp v18, v3 quad_perm:[1,0,3,2] row_mask:0xf bank_mask:0xf
	s_and_saveexec_b64 s[4:5], s[40:41]
	s_cbranch_execz .LBB0_721
	v_add_co_u32_e32 v84, vcc, 0x1000, v82
	v_cvt_pk_bf16_f32 v3, v3, v18
	v_addc_co_u32_e32 v85, vcc, 0, v83, vcc
	global_store_dword v[84:85], v3, off
.LBB0_721:
	s_or_b64 exec, exec, s[4:5]
	v_mul_f32_e32 v3, v51, v2
	s_nop 1
	v_mov_b32_dpp v18, v3 quad_perm:[1,0,3,2] row_mask:0xf bank_mask:0xf
	s_and_saveexec_b64 s[4:5], s[40:41]
	s_cbranch_execz .LBB0_723
	v_add_co_u32_e32 v50, vcc, 0x1000, v82
	v_cvt_pk_bf16_f32 v3, v3, v18
	v_addc_co_u32_e32 v51, vcc, 0, v83, vcc
	global_store_dword v[50:51], v3, off offset:64
.LBB0_723:
	s_or_b64 exec, exec, s[4:5]
	v_mul_f32_e32 v3, v35, v2
	s_nop 1
	v_mov_b32_dpp v18, v3 quad_perm:[1,0,3,2] row_mask:0xf bank_mask:0xf
	s_and_saveexec_b64 s[4:5], s[40:41]
	s_cbranch_execz .LBB0_725
	v_add_co_u32_e32 v34, vcc, 0x1000, v82
	v_cvt_pk_bf16_f32 v3, v3, v18
	v_addc_co_u32_e32 v35, vcc, 0, v83, vcc
	global_store_dword v[34:35], v3, off offset:128
.LBB0_725:
	s_or_b64 exec, exec, s[4:5]
	v_mul_f32_e32 v2, v19, v2
	s_nop 1
	v_mov_b32_dpp v3, v2 quad_perm:[1,0,3,2] row_mask:0xf bank_mask:0xf
	s_and_saveexec_b64 s[4:5], s[40:41]
	s_cbranch_execz .LBB0_727
	v_cvt_pk_bf16_f32 v18, v2, v3
	v_add_co_u32_e32 v2, vcc, 0x1000, v82
	s_nop 1
	v_addc_co_u32_e32 v3, vcc, 0, v83, vcc
	global_store_dword v[2:3], v18, off offset:192
.LBB0_727:
	s_or_b64 exec, exec, s[4:5]
	v_rcp_f32_e32 v2, v80
	s_nop 0
	v_mul_f32_e32 v3, v4, v2
	s_nop 1
	v_mov_b32_dpp v4, v3 quad_perm:[1,0,3,2] row_mask:0xf bank_mask:0xf
	s_and_saveexec_b64 s[4:5], s[40:41]
	s_cbranch_execz .LBB0_729
	v_add_co_u32_e32 v18, vcc, 0x2000, v82
	v_cvt_pk_bf16_f32 v3, v3, v4
	v_addc_co_u32_e32 v19, vcc, 0, v83, vcc
	global_store_dword v[18:19], v3, off
.LBB0_729:
	s_or_b64 exec, exec, s[4:5]
	v_mul_f32_e32 v3, v52, v2
	s_nop 1
	v_mov_b32_dpp v4, v3 quad_perm:[1,0,3,2] row_mask:0xf bank_mask:0xf
	s_and_saveexec_b64 s[4:5], s[40:41]
	s_cbranch_execz .LBB0_731
	v_add_co_u32_e32 v18, vcc, 0x2000, v82
	v_cvt_pk_bf16_f32 v3, v3, v4
	v_addc_co_u32_e32 v19, vcc, 0, v83, vcc
	global_store_dword v[18:19], v3, off offset:64
.LBB0_731:
	s_or_b64 exec, exec, s[4:5]
	v_mul_f32_e32 v3, v36, v2
	s_nop 1
	v_mov_b32_dpp v4, v3 quad_perm:[1,0,3,2] row_mask:0xf bank_mask:0xf
	s_and_saveexec_b64 s[4:5], s[40:41]
	s_cbranch_execz .LBB0_733
	v_add_co_u32_e32 v18, vcc, 0x2000, v82
	v_cvt_pk_bf16_f32 v3, v3, v4
	v_addc_co_u32_e32 v19, vcc, 0, v83, vcc
	global_store_dword v[18:19], v3, off offset:128
.LBB0_733:
	s_or_b64 exec, exec, s[4:5]
	v_mul_f32_e32 v2, v20, v2
	s_nop 1
	v_mov_b32_dpp v3, v2 quad_perm:[1,0,3,2] row_mask:0xf bank_mask:0xf
	s_and_saveexec_b64 s[4:5], s[40:41]
	s_cbranch_execz .LBB0_735
	v_cvt_pk_bf16_f32 v4, v2, v3
	v_add_co_u32_e32 v2, vcc, 0x2000, v82
	s_nop 1
	v_addc_co_u32_e32 v3, vcc, 0, v83, vcc
	global_store_dword v[2:3], v4, off offset:192
.LBB0_735:
	s_or_b64 exec, exec, s[4:5]
	v_rcp_f32_e32 v2, v81
	s_nop 0
	v_mul_f32_e32 v3, v5, v2
	s_nop 1
	v_mov_b32_dpp v4, v3 quad_perm:[1,0,3,2] row_mask:0xf bank_mask:0xf
	s_and_saveexec_b64 s[4:5], s[40:41]
	s_cbranch_execz .LBB0_737
	v_cvt_pk_bf16_f32 v3, v3, v4
	v_add_co_u32_e32 v4, vcc, 0x3000, v82
	s_nop 1
	v_addc_co_u32_e32 v5, vcc, 0, v83, vcc
	global_store_dword v[4:5], v3, off
.LBB0_737:
	s_or_b64 exec, exec, s[4:5]
	v_mul_f32_e32 v3, v53, v2
	s_nop 1
	v_mov_b32_dpp v4, v3 quad_perm:[1,0,3,2] row_mask:0xf bank_mask:0xf
	s_and_saveexec_b64 s[4:5], s[40:41]
	s_cbranch_execz .LBB0_739
	v_cvt_pk_bf16_f32 v3, v3, v4
	v_add_co_u32_e32 v4, vcc, 0x3000, v82
	s_nop 1
	v_addc_co_u32_e32 v5, vcc, 0, v83, vcc
	global_store_dword v[4:5], v3, off offset:64
.LBB0_739:
	s_or_b64 exec, exec, s[4:5]
	v_mul_f32_e32 v3, v37, v2
	s_nop 1
	v_mov_b32_dpp v4, v3 quad_perm:[1,0,3,2] row_mask:0xf bank_mask:0xf
	s_and_saveexec_b64 s[4:5], s[40:41]
	s_cbranch_execz .LBB0_741
	v_cvt_pk_bf16_f32 v3, v3, v4
	v_add_co_u32_e32 v4, vcc, 0x3000, v82
	s_nop 1
	v_addc_co_u32_e32 v5, vcc, 0, v83, vcc
	global_store_dword v[4:5], v3, off offset:128
.LBB0_741:
	s_or_b64 exec, exec, s[4:5]
	v_mul_f32_e32 v2, v21, v2
	s_nop 1
	v_mov_b32_dpp v3, v2 quad_perm:[1,0,3,2] row_mask:0xf bank_mask:0xf
	s_and_saveexec_b64 s[4:5], s[40:41]
	s_cbranch_execz .LBB0_743
	v_cvt_pk_bf16_f32 v4, v2, v3
	v_add_co_u32_e32 v2, vcc, 0x3000, v82
	s_nop 1
	v_addc_co_u32_e32 v3, vcc, 0, v83, vcc
	global_store_dword v[2:3], v4, off offset:192
.LBB0_743:
	s_or_b64 exec, exec, s[4:5]
	v_rcp_f32_e32 v2, v74
	s_nop 0
	v_mul_f32_e32 v3, v6, v2
	s_nop 1
	v_mov_b32_dpp v4, v3 quad_perm:[1,0,3,2] row_mask:0xf bank_mask:0xf
	s_and_saveexec_b64 s[4:5], s[40:41]
	s_cbranch_execz .LBB0_745
	v_cvt_pk_bf16_f32 v3, v3, v4
	v_add_co_u32_e32 v4, vcc, 0x8000, v82
	s_nop 1
	v_addc_co_u32_e32 v5, vcc, 0, v83, vcc
	global_store_dword v[4:5], v3, off
.LBB0_745:
	s_or_b64 exec, exec, s[4:5]
	v_mul_f32_e32 v3, v54, v2
	s_nop 1
	v_mov_b32_dpp v4, v3 quad_perm:[1,0,3,2] row_mask:0xf bank_mask:0xf
	s_and_saveexec_b64 s[4:5], s[40:41]
	s_cbranch_execz .LBB0_747
	v_cvt_pk_bf16_f32 v3, v3, v4
	v_add_co_u32_e32 v4, vcc, 0x8000, v82
	s_nop 1
	v_addc_co_u32_e32 v5, vcc, 0, v83, vcc
	global_store_dword v[4:5], v3, off offset:64
.LBB0_747:
	s_or_b64 exec, exec, s[4:5]
	v_mul_f32_e32 v3, v38, v2
	s_nop 1
	v_mov_b32_dpp v4, v3 quad_perm:[1,0,3,2] row_mask:0xf bank_mask:0xf
	s_and_saveexec_b64 s[4:5], s[40:41]
	s_cbranch_execz .LBB0_749
	v_cvt_pk_bf16_f32 v3, v3, v4
	v_add_co_u32_e32 v4, vcc, 0x8000, v82
	s_nop 1
	v_addc_co_u32_e32 v5, vcc, 0, v83, vcc
	global_store_dword v[4:5], v3, off offset:128
.LBB0_749:
	s_or_b64 exec, exec, s[4:5]
	v_mul_f32_e32 v2, v22, v2
	s_nop 1
	v_mov_b32_dpp v3, v2 quad_perm:[1,0,3,2] row_mask:0xf bank_mask:0xf
	s_and_saveexec_b64 s[4:5], s[40:41]
	s_cbranch_execz .LBB0_751
	v_cvt_pk_bf16_f32 v4, v2, v3
	v_add_co_u32_e32 v2, vcc, 0x8000, v82
	s_nop 1
	v_addc_co_u32_e32 v3, vcc, 0, v83, vcc
	global_store_dword v[2:3], v4, off offset:192
.LBB0_751:
	s_or_b64 exec, exec, s[4:5]
	v_rcp_f32_e32 v2, v75
	s_nop 0
	v_mul_f32_e32 v3, v7, v2
	s_nop 1
	v_mov_b32_dpp v4, v3 quad_perm:[1,0,3,2] row_mask:0xf bank_mask:0xf
	s_and_saveexec_b64 s[4:5], s[40:41]
	s_cbranch_execz .LBB0_753
	v_cvt_pk_bf16_f32 v3, v3, v4
	v_add_co_u32_e32 v4, vcc, 0x9000, v82
	s_nop 1
	v_addc_co_u32_e32 v5, vcc, 0, v83, vcc
	global_store_dword v[4:5], v3, off
.LBB0_753:
	s_or_b64 exec, exec, s[4:5]
	v_mul_f32_e32 v3, v55, v2
	s_nop 1
	v_mov_b32_dpp v4, v3 quad_perm:[1,0,3,2] row_mask:0xf bank_mask:0xf
	s_and_saveexec_b64 s[4:5], s[40:41]
	s_cbranch_execz .LBB0_755
	v_cvt_pk_bf16_f32 v3, v3, v4
	v_add_co_u32_e32 v4, vcc, 0x9000, v82
	s_nop 1
	v_addc_co_u32_e32 v5, vcc, 0, v83, vcc
	global_store_dword v[4:5], v3, off offset:64
.LBB0_755:
	s_or_b64 exec, exec, s[4:5]
	v_mul_f32_e32 v3, v39, v2
	s_nop 1
	v_mov_b32_dpp v4, v3 quad_perm:[1,0,3,2] row_mask:0xf bank_mask:0xf
	s_and_saveexec_b64 s[4:5], s[40:41]
	s_cbranch_execz .LBB0_757
	v_cvt_pk_bf16_f32 v3, v3, v4
	v_add_co_u32_e32 v4, vcc, 0x9000, v82
	s_nop 1
	v_addc_co_u32_e32 v5, vcc, 0, v83, vcc
	global_store_dword v[4:5], v3, off offset:128
.LBB0_757:
	s_or_b64 exec, exec, s[4:5]
	v_mul_f32_e32 v2, v23, v2
	s_nop 1
	v_mov_b32_dpp v3, v2 quad_perm:[1,0,3,2] row_mask:0xf bank_mask:0xf
	s_and_saveexec_b64 s[4:5], s[40:41]
	s_cbranch_execz .LBB0_759
	v_cvt_pk_bf16_f32 v4, v2, v3
	v_add_co_u32_e32 v2, vcc, 0x9000, v82
	s_nop 1
	v_addc_co_u32_e32 v3, vcc, 0, v83, vcc
	global_store_dword v[2:3], v4, off offset:192
.LBB0_759:
	s_or_b64 exec, exec, s[4:5]
	v_rcp_f32_e32 v2, v76
	s_nop 0
	v_mul_f32_e32 v3, v8, v2
	s_nop 1
	v_mov_b32_dpp v4, v3 quad_perm:[1,0,3,2] row_mask:0xf bank_mask:0xf
	s_and_saveexec_b64 s[4:5], s[40:41]
	s_cbranch_execz .LBB0_761
	v_cvt_pk_bf16_f32 v3, v3, v4
	v_add_co_u32_e32 v4, vcc, 0xa000, v82
	s_nop 1
	v_addc_co_u32_e32 v5, vcc, 0, v83, vcc
	global_store_dword v[4:5], v3, off
.LBB0_761:
	s_or_b64 exec, exec, s[4:5]
	v_mul_f32_e32 v3, v56, v2
	s_nop 1
	v_mov_b32_dpp v4, v3 quad_perm:[1,0,3,2] row_mask:0xf bank_mask:0xf
	s_and_saveexec_b64 s[4:5], s[40:41]
	s_cbranch_execz .LBB0_763
	v_cvt_pk_bf16_f32 v3, v3, v4
	v_add_co_u32_e32 v4, vcc, 0xa000, v82
	s_nop 1
	v_addc_co_u32_e32 v5, vcc, 0, v83, vcc
	global_store_dword v[4:5], v3, off offset:64
.LBB0_763:
	s_or_b64 exec, exec, s[4:5]
	v_mul_f32_e32 v3, v40, v2
	s_nop 1
	v_mov_b32_dpp v4, v3 quad_perm:[1,0,3,2] row_mask:0xf bank_mask:0xf
	s_and_saveexec_b64 s[4:5], s[40:41]
	s_cbranch_execz .LBB0_765
	v_cvt_pk_bf16_f32 v3, v3, v4
	v_add_co_u32_e32 v4, vcc, 0xa000, v82
	s_nop 1
	v_addc_co_u32_e32 v5, vcc, 0, v83, vcc
	global_store_dword v[4:5], v3, off offset:128
.LBB0_765:
	s_or_b64 exec, exec, s[4:5]
	v_mul_f32_e32 v2, v24, v2
	s_nop 1
	v_mov_b32_dpp v3, v2 quad_perm:[1,0,3,2] row_mask:0xf bank_mask:0xf
	s_and_saveexec_b64 s[4:5], s[40:41]
	s_cbranch_execz .LBB0_767
	v_cvt_pk_bf16_f32 v4, v2, v3
	v_add_co_u32_e32 v2, vcc, 0xa000, v82
	s_nop 1
	v_addc_co_u32_e32 v3, vcc, 0, v83, vcc
	global_store_dword v[2:3], v4, off offset:192
.LBB0_767:
	s_or_b64 exec, exec, s[4:5]
	v_rcp_f32_e32 v2, v77
	s_nop 0
	v_mul_f32_e32 v3, v9, v2
	s_nop 1
	v_mov_b32_dpp v4, v3 quad_perm:[1,0,3,2] row_mask:0xf bank_mask:0xf
	s_and_saveexec_b64 s[4:5], s[40:41]
	s_cbranch_execz .LBB0_769
	v_cvt_pk_bf16_f32 v3, v3, v4
	v_add_co_u32_e32 v4, vcc, 0xb000, v82
	s_nop 1
	v_addc_co_u32_e32 v5, vcc, 0, v83, vcc
	global_store_dword v[4:5], v3, off
.LBB0_769:
	s_or_b64 exec, exec, s[4:5]
	v_mul_f32_e32 v3, v57, v2
	s_nop 1
	v_mov_b32_dpp v4, v3 quad_perm:[1,0,3,2] row_mask:0xf bank_mask:0xf
	s_and_saveexec_b64 s[4:5], s[40:41]
	s_cbranch_execz .LBB0_771
	v_cvt_pk_bf16_f32 v3, v3, v4
	v_add_co_u32_e32 v4, vcc, 0xb000, v82
	s_nop 1
	v_addc_co_u32_e32 v5, vcc, 0, v83, vcc
	global_store_dword v[4:5], v3, off offset:64
.LBB0_771:
	s_or_b64 exec, exec, s[4:5]
	v_mul_f32_e32 v3, v41, v2
	s_nop 1
	v_mov_b32_dpp v4, v3 quad_perm:[1,0,3,2] row_mask:0xf bank_mask:0xf
	s_and_saveexec_b64 s[4:5], s[40:41]
	s_cbranch_execz .LBB0_773
	v_cvt_pk_bf16_f32 v3, v3, v4
	v_add_co_u32_e32 v4, vcc, 0xb000, v82
	s_nop 1
	v_addc_co_u32_e32 v5, vcc, 0, v83, vcc
	global_store_dword v[4:5], v3, off offset:128
.LBB0_773:
	s_or_b64 exec, exec, s[4:5]
	v_mul_f32_e32 v2, v25, v2
	s_nop 1
	v_mov_b32_dpp v3, v2 quad_perm:[1,0,3,2] row_mask:0xf bank_mask:0xf
	s_and_saveexec_b64 s[4:5], s[40:41]
	s_cbranch_execz .LBB0_775
	v_cvt_pk_bf16_f32 v4, v2, v3
	v_add_co_u32_e32 v2, vcc, 0xb000, v82
	s_nop 1
	v_addc_co_u32_e32 v3, vcc, 0, v83, vcc
	global_store_dword v[2:3], v4, off offset:192
.LBB0_775:
	s_or_b64 exec, exec, s[4:5]
	v_rcp_f32_e32 v2, v70
	s_nop 0
	v_mul_f32_e32 v3, v10, v2
	s_nop 1
	v_mov_b32_dpp v4, v3 quad_perm:[1,0,3,2] row_mask:0xf bank_mask:0xf
	s_and_saveexec_b64 s[4:5], s[40:41]
	s_cbranch_execz .LBB0_777
	v_cvt_pk_bf16_f32 v3, v3, v4
	v_add_co_u32_e32 v4, vcc, 0x10000, v82
	s_nop 1
	v_addc_co_u32_e32 v5, vcc, 0, v83, vcc
	global_store_dword v[4:5], v3, off
.LBB0_777:
	s_or_b64 exec, exec, s[4:5]
	v_mul_f32_e32 v3, v58, v2
	s_nop 1
	v_mov_b32_dpp v4, v3 quad_perm:[1,0,3,2] row_mask:0xf bank_mask:0xf
	s_and_saveexec_b64 s[4:5], s[40:41]
	s_cbranch_execz .LBB0_779
	v_cvt_pk_bf16_f32 v3, v3, v4
	v_add_co_u32_e32 v4, vcc, 0x10000, v82
	s_nop 1
	v_addc_co_u32_e32 v5, vcc, 0, v83, vcc
	global_store_dword v[4:5], v3, off offset:64
.LBB0_779:
	s_or_b64 exec, exec, s[4:5]
	v_mul_f32_e32 v3, v42, v2
	s_nop 1
	v_mov_b32_dpp v4, v3 quad_perm:[1,0,3,2] row_mask:0xf bank_mask:0xf
	s_and_saveexec_b64 s[4:5], s[40:41]
	s_cbranch_execz .LBB0_781
	v_cvt_pk_bf16_f32 v3, v3, v4
	v_add_co_u32_e32 v4, vcc, 0x10000, v82
	s_nop 1
	v_addc_co_u32_e32 v5, vcc, 0, v83, vcc
	global_store_dword v[4:5], v3, off offset:128
.LBB0_781:
	s_or_b64 exec, exec, s[4:5]
	v_mul_f32_e32 v2, v26, v2
	s_nop 1
	v_mov_b32_dpp v3, v2 quad_perm:[1,0,3,2] row_mask:0xf bank_mask:0xf
	s_and_saveexec_b64 s[4:5], s[40:41]
	s_cbranch_execz .LBB0_783
	v_cvt_pk_bf16_f32 v4, v2, v3
	v_add_co_u32_e32 v2, vcc, 0x10000, v82
	s_nop 1
	v_addc_co_u32_e32 v3, vcc, 0, v83, vcc
	global_store_dword v[2:3], v4, off offset:192
.LBB0_783:
	s_or_b64 exec, exec, s[4:5]
	v_rcp_f32_e32 v2, v71
	s_nop 0
	v_mul_f32_e32 v3, v11, v2
	s_nop 1
	v_mov_b32_dpp v4, v3 quad_perm:[1,0,3,2] row_mask:0xf bank_mask:0xf
	s_and_saveexec_b64 s[4:5], s[40:41]
	s_cbranch_execz .LBB0_785
	v_cvt_pk_bf16_f32 v3, v3, v4
	v_add_co_u32_e32 v4, vcc, 0x11000, v82
	s_nop 1
	v_addc_co_u32_e32 v5, vcc, 0, v83, vcc
	global_store_dword v[4:5], v3, off
.LBB0_785:
	s_or_b64 exec, exec, s[4:5]
	v_mul_f32_e32 v3, v59, v2
	s_nop 1
	v_mov_b32_dpp v4, v3 quad_perm:[1,0,3,2] row_mask:0xf bank_mask:0xf
	s_and_saveexec_b64 s[4:5], s[40:41]
	s_cbranch_execz .LBB0_787
	v_cvt_pk_bf16_f32 v3, v3, v4
	v_add_co_u32_e32 v4, vcc, 0x11000, v82
	s_nop 1
	v_addc_co_u32_e32 v5, vcc, 0, v83, vcc
	global_store_dword v[4:5], v3, off offset:64
.LBB0_787:
	s_or_b64 exec, exec, s[4:5]
	v_mul_f32_e32 v3, v43, v2
	s_nop 1
	v_mov_b32_dpp v4, v3 quad_perm:[1,0,3,2] row_mask:0xf bank_mask:0xf
	s_and_saveexec_b64 s[4:5], s[40:41]
	s_cbranch_execz .LBB0_789
	v_cvt_pk_bf16_f32 v3, v3, v4
	v_add_co_u32_e32 v4, vcc, 0x11000, v82
	s_nop 1
	v_addc_co_u32_e32 v5, vcc, 0, v83, vcc
	global_store_dword v[4:5], v3, off offset:128
.LBB0_789:
	s_or_b64 exec, exec, s[4:5]
	v_mul_f32_e32 v2, v27, v2
	s_nop 1
	v_mov_b32_dpp v3, v2 quad_perm:[1,0,3,2] row_mask:0xf bank_mask:0xf
	s_and_saveexec_b64 s[4:5], s[40:41]
	s_cbranch_execz .LBB0_791
	v_cvt_pk_bf16_f32 v4, v2, v3
	v_add_co_u32_e32 v2, vcc, 0x11000, v82
	s_nop 1
	v_addc_co_u32_e32 v3, vcc, 0, v83, vcc
	global_store_dword v[2:3], v4, off offset:192
.LBB0_791:
	s_or_b64 exec, exec, s[4:5]
	v_rcp_f32_e32 v2, v72
	s_nop 0
	v_mul_f32_e32 v3, v12, v2
	s_nop 1
	v_mov_b32_dpp v4, v3 quad_perm:[1,0,3,2] row_mask:0xf bank_mask:0xf
	s_and_saveexec_b64 s[4:5], s[40:41]
	s_cbranch_execz .LBB0_793
	v_cvt_pk_bf16_f32 v3, v3, v4
	v_add_co_u32_e32 v4, vcc, 0x12000, v82
	s_nop 1
	v_addc_co_u32_e32 v5, vcc, 0, v83, vcc
	global_store_dword v[4:5], v3, off
.LBB0_793:
	s_or_b64 exec, exec, s[4:5]
	v_mul_f32_e32 v3, v60, v2
	s_nop 1
	v_mov_b32_dpp v4, v3 quad_perm:[1,0,3,2] row_mask:0xf bank_mask:0xf
	s_and_saveexec_b64 s[4:5], s[40:41]
	s_cbranch_execz .LBB0_795
	v_cvt_pk_bf16_f32 v3, v3, v4
	v_add_co_u32_e32 v4, vcc, 0x12000, v82
	s_nop 1
	v_addc_co_u32_e32 v5, vcc, 0, v83, vcc
	global_store_dword v[4:5], v3, off offset:64
.LBB0_795:
	s_or_b64 exec, exec, s[4:5]
	v_mul_f32_e32 v3, v44, v2
	s_nop 1
	v_mov_b32_dpp v4, v3 quad_perm:[1,0,3,2] row_mask:0xf bank_mask:0xf
	s_and_saveexec_b64 s[4:5], s[40:41]
	s_cbranch_execz .LBB0_797
	v_cvt_pk_bf16_f32 v3, v3, v4
	v_add_co_u32_e32 v4, vcc, 0x12000, v82
	s_nop 1
	v_addc_co_u32_e32 v5, vcc, 0, v83, vcc
	global_store_dword v[4:5], v3, off offset:128
.LBB0_797:
	s_or_b64 exec, exec, s[4:5]
	v_mul_f32_e32 v2, v28, v2
	s_nop 1
	v_mov_b32_dpp v3, v2 quad_perm:[1,0,3,2] row_mask:0xf bank_mask:0xf
	s_and_saveexec_b64 s[4:5], s[40:41]
	s_cbranch_execz .LBB0_799
	v_cvt_pk_bf16_f32 v4, v2, v3
	v_add_co_u32_e32 v2, vcc, 0x12000, v82
	s_nop 1
	v_addc_co_u32_e32 v3, vcc, 0, v83, vcc
	global_store_dword v[2:3], v4, off offset:192
.LBB0_799:
	s_or_b64 exec, exec, s[4:5]
	v_rcp_f32_e32 v2, v73
	s_nop 0
	v_mul_f32_e32 v3, v13, v2
	s_nop 1
	v_mov_b32_dpp v4, v3 quad_perm:[1,0,3,2] row_mask:0xf bank_mask:0xf
	s_and_saveexec_b64 s[4:5], s[40:41]
	s_cbranch_execz .LBB0_801
	v_cvt_pk_bf16_f32 v3, v3, v4
	v_add_co_u32_e32 v4, vcc, 0x13000, v82
	s_nop 1
	v_addc_co_u32_e32 v5, vcc, 0, v83, vcc
	global_store_dword v[4:5], v3, off
.LBB0_801:
	s_or_b64 exec, exec, s[4:5]
	v_mul_f32_e32 v3, v61, v2
	s_nop 1
	v_mov_b32_dpp v4, v3 quad_perm:[1,0,3,2] row_mask:0xf bank_mask:0xf
	s_and_saveexec_b64 s[4:5], s[40:41]
	s_cbranch_execz .LBB0_803
	v_cvt_pk_bf16_f32 v3, v3, v4
	v_add_co_u32_e32 v4, vcc, 0x13000, v82
	s_nop 1
	v_addc_co_u32_e32 v5, vcc, 0, v83, vcc
	global_store_dword v[4:5], v3, off offset:64
.LBB0_803:
	s_or_b64 exec, exec, s[4:5]
	v_mul_f32_e32 v3, v45, v2
	s_nop 1
	v_mov_b32_dpp v4, v3 quad_perm:[1,0,3,2] row_mask:0xf bank_mask:0xf
	s_and_saveexec_b64 s[4:5], s[40:41]
	s_cbranch_execz .LBB0_805
	v_cvt_pk_bf16_f32 v3, v3, v4
	v_add_co_u32_e32 v4, vcc, 0x13000, v82
	s_nop 1
	v_addc_co_u32_e32 v5, vcc, 0, v83, vcc
	global_store_dword v[4:5], v3, off offset:128
.LBB0_805:
	s_or_b64 exec, exec, s[4:5]
	v_mul_f32_e32 v2, v29, v2
	s_nop 1
	v_mov_b32_dpp v3, v2 quad_perm:[1,0,3,2] row_mask:0xf bank_mask:0xf
	s_and_saveexec_b64 s[4:5], s[40:41]
	s_cbranch_execz .LBB0_807
	v_cvt_pk_bf16_f32 v4, v2, v3
	v_add_co_u32_e32 v2, vcc, 0x13000, v82
	s_nop 1
	v_addc_co_u32_e32 v3, vcc, 0, v83, vcc
	global_store_dword v[2:3], v4, off offset:192
.LBB0_807:
	s_or_b64 exec, exec, s[4:5]
	v_rcp_f32_e32 v2, v66
	s_nop 0
	v_mul_f32_e32 v3, v14, v2
	s_nop 1
	v_mov_b32_dpp v4, v3 quad_perm:[1,0,3,2] row_mask:0xf bank_mask:0xf
	s_and_saveexec_b64 s[4:5], s[40:41]
	s_cbranch_execz .LBB0_809
	v_cvt_pk_bf16_f32 v3, v3, v4
	v_add_co_u32_e32 v4, vcc, 0x18000, v82
	s_nop 1
	v_addc_co_u32_e32 v5, vcc, 0, v83, vcc
	global_store_dword v[4:5], v3, off
.LBB0_809:
	s_or_b64 exec, exec, s[4:5]
	v_mul_f32_e32 v3, v62, v2
	s_nop 1
	v_mov_b32_dpp v4, v3 quad_perm:[1,0,3,2] row_mask:0xf bank_mask:0xf
	s_and_saveexec_b64 s[4:5], s[40:41]
	s_cbranch_execz .LBB0_811
	v_cvt_pk_bf16_f32 v3, v3, v4
	v_add_co_u32_e32 v4, vcc, 0x18000, v82
	s_nop 1
	v_addc_co_u32_e32 v5, vcc, 0, v83, vcc
	global_store_dword v[4:5], v3, off offset:64
.LBB0_811:
	s_or_b64 exec, exec, s[4:5]
	v_mul_f32_e32 v3, v46, v2
	s_nop 1
	v_mov_b32_dpp v4, v3 quad_perm:[1,0,3,2] row_mask:0xf bank_mask:0xf
	s_and_saveexec_b64 s[4:5], s[40:41]
	s_cbranch_execz .LBB0_813
	v_cvt_pk_bf16_f32 v3, v3, v4
	v_add_co_u32_e32 v4, vcc, 0x18000, v82
	s_nop 1
	v_addc_co_u32_e32 v5, vcc, 0, v83, vcc
	global_store_dword v[4:5], v3, off offset:128
.LBB0_813:
	s_or_b64 exec, exec, s[4:5]
	v_mul_f32_e32 v2, v30, v2
	s_nop 1
	v_mov_b32_dpp v3, v2 quad_perm:[1,0,3,2] row_mask:0xf bank_mask:0xf
	s_and_saveexec_b64 s[4:5], s[40:41]
	s_cbranch_execz .LBB0_815
	v_cvt_pk_bf16_f32 v4, v2, v3
	v_add_co_u32_e32 v2, vcc, 0x18000, v82
	s_nop 1
	v_addc_co_u32_e32 v3, vcc, 0, v83, vcc
	global_store_dword v[2:3], v4, off offset:192
.LBB0_815:
	s_or_b64 exec, exec, s[4:5]
	v_rcp_f32_e32 v2, v67
	s_nop 0
	v_mul_f32_e32 v3, v15, v2
	s_nop 1
	v_mov_b32_dpp v4, v3 quad_perm:[1,0,3,2] row_mask:0xf bank_mask:0xf
	s_and_saveexec_b64 s[4:5], s[40:41]
	s_cbranch_execz .LBB0_817
	v_cvt_pk_bf16_f32 v3, v3, v4
	v_add_co_u32_e32 v4, vcc, 0x19000, v82
	s_nop 1
	v_addc_co_u32_e32 v5, vcc, 0, v83, vcc
	global_store_dword v[4:5], v3, off
.LBB0_817:
	s_or_b64 exec, exec, s[4:5]
	v_mul_f32_e32 v3, v63, v2
	s_nop 1
	v_mov_b32_dpp v4, v3 quad_perm:[1,0,3,2] row_mask:0xf bank_mask:0xf
	s_and_saveexec_b64 s[4:5], s[40:41]
	s_cbranch_execz .LBB0_819
	v_cvt_pk_bf16_f32 v3, v3, v4
	v_add_co_u32_e32 v4, vcc, 0x19000, v82
	s_nop 1
	v_addc_co_u32_e32 v5, vcc, 0, v83, vcc
	global_store_dword v[4:5], v3, off offset:64
.LBB0_819:
	s_or_b64 exec, exec, s[4:5]
	v_mul_f32_e32 v3, v47, v2
	s_nop 1
	v_mov_b32_dpp v4, v3 quad_perm:[1,0,3,2] row_mask:0xf bank_mask:0xf
	s_and_saveexec_b64 s[4:5], s[40:41]
	s_cbranch_execz .LBB0_821
	v_cvt_pk_bf16_f32 v3, v3, v4
	v_add_co_u32_e32 v4, vcc, 0x19000, v82
	s_nop 1
	v_addc_co_u32_e32 v5, vcc, 0, v83, vcc
	global_store_dword v[4:5], v3, off offset:128
.LBB0_821:
	s_or_b64 exec, exec, s[4:5]
	v_mul_f32_e32 v2, v31, v2
	s_nop 1
	v_mov_b32_dpp v3, v2 quad_perm:[1,0,3,2] row_mask:0xf bank_mask:0xf
	s_and_saveexec_b64 s[4:5], s[40:41]
	s_cbranch_execz .LBB0_823
	v_cvt_pk_bf16_f32 v4, v2, v3
	v_add_co_u32_e32 v2, vcc, 0x19000, v82
	s_nop 1
	v_addc_co_u32_e32 v3, vcc, 0, v83, vcc
	global_store_dword v[2:3], v4, off offset:192
.LBB0_823:
	s_or_b64 exec, exec, s[4:5]
	v_rcp_f32_e32 v2, v68
	s_nop 0
	v_mul_f32_e32 v3, v16, v2
	s_nop 1
	v_mov_b32_dpp v4, v3 quad_perm:[1,0,3,2] row_mask:0xf bank_mask:0xf
	s_and_saveexec_b64 s[4:5], s[40:41]
	s_cbranch_execz .LBB0_825
	v_cvt_pk_bf16_f32 v3, v3, v4
	v_add_co_u32_e32 v4, vcc, 0x1a000, v82
	s_nop 1
	v_addc_co_u32_e32 v5, vcc, 0, v83, vcc
	global_store_dword v[4:5], v3, off
.LBB0_825:
	s_or_b64 exec, exec, s[4:5]
	v_mul_f32_e32 v3, v64, v2
	s_nop 1
	v_mov_b32_dpp v4, v3 quad_perm:[1,0,3,2] row_mask:0xf bank_mask:0xf
	s_and_saveexec_b64 s[4:5], s[40:41]
	s_cbranch_execz .LBB0_827
	v_cvt_pk_bf16_f32 v3, v3, v4
	v_add_co_u32_e32 v4, vcc, 0x1a000, v82
	s_nop 1
	v_addc_co_u32_e32 v5, vcc, 0, v83, vcc
	global_store_dword v[4:5], v3, off offset:64
.LBB0_827:
	s_or_b64 exec, exec, s[4:5]
	v_mul_f32_e32 v3, v48, v2
	s_nop 1
	v_mov_b32_dpp v4, v3 quad_perm:[1,0,3,2] row_mask:0xf bank_mask:0xf
	s_and_saveexec_b64 s[4:5], s[40:41]
	s_cbranch_execz .LBB0_829
	v_cvt_pk_bf16_f32 v3, v3, v4
	v_add_co_u32_e32 v4, vcc, 0x1a000, v82
	s_nop 1
	v_addc_co_u32_e32 v5, vcc, 0, v83, vcc
	global_store_dword v[4:5], v3, off offset:128
.LBB0_829:
	s_or_b64 exec, exec, s[4:5]
	v_mul_f32_e32 v2, v32, v2
	s_nop 1
	v_mov_b32_dpp v3, v2 quad_perm:[1,0,3,2] row_mask:0xf bank_mask:0xf
	s_and_saveexec_b64 s[4:5], s[40:41]
	s_cbranch_execz .LBB0_831
	v_cvt_pk_bf16_f32 v4, v2, v3
	v_add_co_u32_e32 v2, vcc, 0x1a000, v82
	s_nop 1
	v_addc_co_u32_e32 v3, vcc, 0, v83, vcc
	global_store_dword v[2:3], v4, off offset:192
.LBB0_831:
	s_or_b64 exec, exec, s[4:5]
	v_rcp_f32_e32 v2, v69
	s_nop 0
	v_mul_f32_e32 v3, v17, v2
	s_nop 1
	v_mov_b32_dpp v4, v3 quad_perm:[1,0,3,2] row_mask:0xf bank_mask:0xf
	s_and_saveexec_b64 s[4:5], s[40:41]
	s_cbranch_execz .LBB0_833
	v_cvt_pk_bf16_f32 v3, v3, v4
	v_add_co_u32_e32 v4, vcc, 0x1b000, v82
	s_nop 1
	v_addc_co_u32_e32 v5, vcc, 0, v83, vcc
	global_store_dword v[4:5], v3, off
.LBB0_833:
	s_or_b64 exec, exec, s[4:5]
	v_mul_f32_e32 v3, v65, v2
	s_nop 1
	v_mov_b32_dpp v4, v3 quad_perm:[1,0,3,2] row_mask:0xf bank_mask:0xf
	s_and_saveexec_b64 s[4:5], s[40:41]
	s_cbranch_execz .LBB0_835
	v_cvt_pk_bf16_f32 v3, v3, v4
	v_add_co_u32_e32 v4, vcc, 0x1b000, v82
	s_nop 1
	v_addc_co_u32_e32 v5, vcc, 0, v83, vcc
	global_store_dword v[4:5], v3, off offset:64
.LBB0_835:
	s_or_b64 exec, exec, s[4:5]
	v_mul_f32_e32 v3, v49, v2
	s_nop 1
	v_mov_b32_dpp v4, v3 quad_perm:[1,0,3,2] row_mask:0xf bank_mask:0xf
	s_and_saveexec_b64 s[4:5], s[40:41]
	s_cbranch_execz .LBB0_837
	v_cvt_pk_bf16_f32 v3, v3, v4
	v_add_co_u32_e32 v4, vcc, 0x1b000, v82
	s_nop 1
	v_addc_co_u32_e32 v5, vcc, 0, v83, vcc
	global_store_dword v[4:5], v3, off offset:128
.LBB0_837:
	s_or_b64 exec, exec, s[4:5]
	v_mul_f32_e32 v2, v33, v2
	s_nop 1
	v_mov_b32_dpp v3, v2 quad_perm:[1,0,3,2] row_mask:0xf bank_mask:0xf
	s_and_saveexec_b64 s[4:5], s[40:41]
	s_cbranch_execz .LBB0_476
	v_cvt_pk_bf16_f32 v4, v2, v3
	v_add_co_u32_e32 v2, vcc, 0x1b000, v82
	s_nop 1
	v_addc_co_u32_e32 v3, vcc, 0, v83, vcc
	global_store_dword v[2:3], v4, off offset:192
	s_branch .LBB0_476

.LBB0_864:
	s_or_b64 exec, exec, s[14:15]
	v_add_f32_e32 v136, v159, v137
	v_mul_f32_e32 v136, 0xbfb8aa3b, v136
	v_exp_f32_e32 v136, v136
	ds_read_u16 v137, v182 offset:816
	v_sqrt_f32_e32 v135, v135
	v_lshl_add_u32 v138, v173, 2, s12
	v_add_f32_e32 v136, 1.0, v136
	v_rcp_f32_e32 v136, v136
	s_waitcnt lgkmcnt(0)
	v_lshlrev_b32_e32 v137, 16, v137
	s_waitcnt vmcnt(7)
	v_lshlrev_b32_e32 v190, 16, v190
	s_waitcnt vmcnt(6)
	v_lshlrev_b32_e32 v189, 16, v189
	v_mul_f32_e32 v136, v136, v137
	v_mul_f32_e32 v135, v135, v136
	ds_write2st64_b32 v138, v134, v135 offset0:136 offset1:208
	v_lshl_add_u32 v134, v163, 2, s12
	s_waitcnt lgkmcnt(0)
	s_barrier
	v_add_u32_e32 v135, 0x8800, v134
	v_add_u32_e32 v136, 0xd000, v134
	ds_read2_b32 v[138:139], v135 offset1:16
	ds_read2_b32 v[140:141], v136 offset1:16
	ds_read2_b32 v[142:143], v135 offset0:32 offset1:48
	ds_read2_b32 v[144:145], v136 offset0:32 offset1:48
	ds_read2_b32 v[146:147], v135 offset0:64 offset1:80
	ds_read2_b32 v[148:149], v136 offset0:64 offset1:80
	s_mov_b32 s12, 0x3dc00000
	s_waitcnt lgkmcnt(3)
	v_mov_b32_e32 v195, v142
	v_mul_f32_e32 v193, v138, v139
	v_fma_f32 v134, 0, v138, v140
	v_fma_f32 v134, v134, v139, v141
	s_waitcnt lgkmcnt(2)
	v_fma_f32 v134, v134, v142, v144
	v_fma_f32 v134, v134, v143, v145
	s_waitcnt lgkmcnt(0)
	v_fma_f32 v192, v134, v146, v148
	ds_read2_b32 v[134:135], v135 offset0:96 offset1:112
	ds_read2_b32 v[136:137], v136 offset0:96 offset1:112
	v_mov_b32_e32 v194, v147
	v_pk_mul_f32 v[196:197], v[192:193], v[194:195]
	v_mov_b32_e32 v198, v149
	v_mov_b32_e32 v200, v149
	v_mov_b32_e32 v201, v143
	v_pk_fma_f32 v[192:193], v[192:193], v[194:195], v[198:199]
	v_pk_mul_f32 v[194:195], v[196:197], v[200:201]
	s_waitcnt lgkmcnt(1)
	v_mov_b32_e32 v196, v134
	v_mov_b32_e32 v197, v146
	v_mov_b32_e32 v193, v195
	v_pk_mul_f32 v[194:195], v[194:195], v[196:197]
	s_waitcnt lgkmcnt(0)
	v_mov_b32_e32 v198, v136
	v_mov_b32_e32 v199, v147
	v_pk_fma_f32 v[192:193], v[192:193], v[196:197], v[136:137]
	v_pk_mul_f32 v[194:195], v[194:195], v[198:199]
	s_addk_i32 s17, 0x80
	v_mov_b32_e32 v193, v195
	v_mov_b32_e32 v194, v135
	v_mov_b32_e32 v195, v134
	v_pk_mul_f32 v[192:193], v[192:193], v[194:195]
	s_mov_b64 s[14:15], 0x80000
	v_mul_f32_e32 v191, v193, v135
	v_add_f32_e32 v192, v192, v137
	s_add_i32 s16, s16, 64
	s_cmpk_lg_i32 s17, 0x800
	v_lshl_add_u64 v[154:155], v[154:155], 0, s[36:37]
	s_nop 1
	v_fmac_f32_dpp v192, v192, v191 row_shr:1 row_mask:0xf bank_mask:0xf
	v_mul_f32_dpp v191, v191, v191 row_shr:1 row_mask:0xf bank_mask:0xf
	s_nop 1
	v_fmac_f32_dpp v192, v192, v191 row_shr:2 row_mask:0xf bank_mask:0xf
	v_mul_f32_dpp v191, v191, v191 row_shr:2 row_mask:0xf bank_mask:0xf
	s_nop 1
	v_fmac_f32_dpp v192, v192, v191 row_shr:4 row_mask:0xf bank_mask:0xf
	v_mul_f32_dpp v191, v191, v191 row_shr:4 row_mask:0xf bank_mask:0xf
	s_nop 1
	v_fmac_f32_dpp v192, v192, v191 row_shr:8 row_mask:0xf bank_mask:0xf
	v_mul_f32_dpp v191, v191, v191 row_shr:8 row_mask:0xf bank_mask:0xf
	v_fmac_f32_e32 v192, v178, v191
	v_mul_f32_e32 v191, v190, v190
	v_fmamk_f32 v191, v191, 0xbdd2d3e7, v228
	v_mul_f32_e32 v191, v191, v190
	v_exp_f32_e32 v191, v191
	v_mov_b32_dpp v193, v192 row_shr:1 row_mask:0xf bank_mask:0xf
	v_add_f32_e32 v191, 1.0, v191
	v_rcp_f32_e32 v191, v191
	v_cndmask_b32_e64 v193, v193, v178, s[42:43]
	v_fma_f32 v138, v138, v193, v140
	ds_bpermute_b32 v178, v165, v192
	v_mul_f32_e32 v140, v191, v190
	v_mul_f32_e32 v190, v189, v189
	v_fmamk_f32 v190, v190, 0xbdd2d3e7, v228
	v_mul_f32_e32 v190, v190, v189
	v_exp_f32_e32 v192, v190
	v_mul_f32_e32 v140, v140, v138
	v_bfe_u32 v190, v140, 16, 1
	v_add3_u32 v140, v140, v190, s0
	v_lshl_add_u64 v[190:191], v[152:153], 0, v[150:151]
	v_add_f32_e32 v192, 1.0, v192
	v_rcp_f32_e32 v194, v192
	v_add_co_u32_e32 v192, vcc, s12, v190
	v_fmac_f32_e32 v141, v139, v138
	s_nop 0
	v_addc_co_u32_e32 v193, vcc, 0, v191, vcc
	global_store_short_d16_hi v[192:193], v140, off offset:3072
	s_waitcnt vmcnt(6)
	v_lshlrev_b32_e32 v140, 16, v188
	v_mul_f32_e32 v139, v140, v140
	v_fmamk_f32 v139, v139, 0xbdd2d3e7, v228
	v_mul_f32_e32 v139, v139, v140
	v_exp_f32_e32 v139, v139
	v_mul_f32_e32 v138, v194, v189
	v_mul_f32_e32 v138, v138, v141
	v_bfe_u32 v188, v138, 16, 1
	v_add3_u32 v188, v138, v188, s0
	v_add_f32_e32 v138, 1.0, v139
	v_rcp_f32_e32 v189, v138
	s_mov_b32 s12, 0x3dc01000
	v_add_co_u32_e32 v138, vcc, s12, v190
	v_fma_f32 v141, v142, v141, v144
	s_nop 0
	v_addc_co_u32_e32 v139, vcc, 0, v191, vcc
	global_store_short_d16_hi v[138:139], v188, off offset:3072
	v_mul_f32_e32 v138, v189, v140
	s_waitcnt vmcnt(6)
	v_lshlrev_b32_e32 v140, 16, v187
	v_mul_f32_e32 v139, v140, v140
	v_fmamk_f32 v139, v139, 0xbdd2d3e7, v228
	v_mul_f32_e32 v139, v139, v140
	v_exp_f32_e32 v139, v139
	v_mul_f32_e32 v138, v138, v141
	v_bfe_u32 v142, v138, 16, 1
	v_add3_u32 v142, v138, v142, s0
	v_add_f32_e32 v138, 1.0, v139
	v_rcp_f32_e32 v144, v138
	s_mov_b32 s12, 0x3dc02000
	v_add_co_u32_e32 v138, vcc, s12, v190
	v_fmac_f32_e32 v145, v143, v141
	s_nop 0
	v_addc_co_u32_e32 v139, vcc, 0, v191, vcc
	global_store_short_d16_hi v[138:139], v142, off offset:3072
	v_mul_f32_e32 v138, v144, v140
	s_waitcnt vmcnt(6)
	v_lshlrev_b32_e32 v140, 16, v186
	v_mul_f32_e32 v139, v140, v140
	v_fmamk_f32 v139, v139, 0xbdd2d3e7, v228
	v_mul_f32_e32 v139, v139, v140
	v_exp_f32_e32 v139, v139
	v_mul_f32_e32 v138, v138, v145
	v_bfe_u32 v141, v138, 16, 1
	v_add3_u32 v141, v138, v141, s0
	v_add_f32_e32 v138, 1.0, v139
	v_rcp_f32_e32 v142, v138
	s_mov_b32 s12, 0x3dc03000
	v_add_co_u32_e32 v138, vcc, s12, v190
	s_mov_b32 s12, 0x3dc04000
	s_nop 0
	v_addc_co_u32_e32 v139, vcc, 0, v191, vcc
	global_store_short_d16_hi v[138:139], v141, off offset:3072
	v_mul_f32_e32 v138, v142, v140
	s_waitcnt vmcnt(6)
	v_lshlrev_b32_e32 v140, 16, v185
	v_mul_f32_e32 v139, v140, v140
	v_fmamk_f32 v139, v139, 0xbdd2d3e7, v228
	v_mul_f32_e32 v139, v139, v140
	v_exp_f32_e32 v139, v139
	v_fma_f32 v141, v146, v145, v148
	v_mul_f32_e32 v138, v138, v141
	v_bfe_u32 v142, v138, 16, 1
	v_add3_u32 v142, v138, v142, s0
	v_add_f32_e32 v138, 1.0, v139
	v_rcp_f32_e32 v143, v138
	v_add_co_u32_e32 v138, vcc, s12, v190
	v_fmac_f32_e32 v149, v147, v141
	s_nop 0
	v_addc_co_u32_e32 v139, vcc, 0, v191, vcc
	global_store_short_d16_hi v[138:139], v142, off offset:3072
	v_mul_f32_e32 v138, v143, v140
	s_waitcnt vmcnt(6)
	v_lshlrev_b32_e32 v140, 16, v183
	v_mul_f32_e32 v139, v140, v140
	v_fmamk_f32 v139, v139, 0xbdd2d3e7, v228
	v_mul_f32_e32 v139, v139, v140
	v_exp_f32_e32 v139, v139
	v_mul_f32_e32 v138, v138, v149
	v_bfe_u32 v141, v138, 16, 1
	v_add3_u32 v141, v138, v141, s0
	v_add_f32_e32 v138, 1.0, v139
	v_rcp_f32_e32 v142, v138
	s_mov_b32 s12, 0x3dc05000
	v_add_co_u32_e32 v138, vcc, s12, v190
	v_fma_f32 v134, v134, v149, v136
	s_nop 0
	v_addc_co_u32_e32 v139, vcc, 0, v191, vcc
	v_mul_f32_e32 v136, v142, v140
	s_waitcnt vmcnt(5)
	v_lshlrev_b32_e32 v140, 16, v184
	global_store_short_d16_hi v[138:139], v141, off offset:3072
	v_mul_f32_e32 v138, v140, v140
	v_fmamk_f32 v138, v138, 0xbdd2d3e7, v228
	v_mul_f32_e32 v138, v138, v140
	v_exp_f32_e32 v138, v138
	v_mul_f32_e32 v136, v136, v134
	s_mov_b32 s12, 0x3dc06000
	v_fmac_f32_e32 v137, v135, v134
	v_add_f32_e32 v138, 1.0, v138
	v_rcp_f32_e32 v141, v138
	v_bfe_u32 v139, v136, 16, 1
	v_add_co_u32_e32 v138, vcc, s12, v190
	v_mul_f32_e32 v134, v141, v140
	v_mul_f32_e32 v134, v134, v137
	v_add3_u32 v136, v136, v139, s0
	v_addc_co_u32_e32 v139, vcc, 0, v191, vcc
	v_bfe_u32 v135, v134, 16, 1
	global_store_short_d16_hi v[138:139], v136, off offset:3072
	v_add3_u32 v136, v134, v135, s0
	v_add_co_u32_e32 v134, vcc, 0x3dc07000, v190
	v_lshl_add_u64 v[152:153], v[152:153], 0, s[14:15]
	s_nop 0
	v_addc_co_u32_e32 v135, vcc, 0, v191, vcc
	global_store_short_d16_hi v[134:135], v136, off offset:3072
	s_cbranch_scc0 .LBB0_848
